# all loop stores write-through (sc1); grid barriers inside the layer loop drop the L2 write-back
# speedup vs baseline: 1.0072x; 1.0072x over previous
.LBB0_434:
	v_and_b32_e32 v14, -4, v8
	v_and_b32_e32 v15, -4, v9
	v_add_u32_e32 v14, v5, v14
	v_add_u32_e32 v16, v5, v15
	ds_read2st64_b32 v[14:15], v14 offset1:4
	ds_read2st64_b32 v[16:17], v16 offset1:4
	v_ashrrev_i32_e32 v13, 2, v8
	v_ashrrev_i32_e32 v3, 2, v9
	v_add_u32_e32 v12, -4, v12
	s_waitcnt lgkmcnt(1)
	v_mov_b32_e32 v18, v14
	s_waitcnt lgkmcnt(0)
	v_mov_b32_e32 v19, v16
	v_mov_b32_e32 v16, v15
	v_pk_add_f32 v[14:15], v[18:19], v[16:17]
	v_add_u32_e32 v16, s4, v13
	v_add_u32_e32 v18, s4, v3
	v_ashrrev_i32_e32 v17, 31, v16
	v_add_u32_e32 v3, 0x400, v8
	v_ashrrev_i32_e32 v19, 31, v18
	v_lshl_add_u64 v[16:17], v[16:17], 2, v[6:7]
	v_add_u32_e32 v13, 0x400, v9
	v_ashrrev_i32_e32 v21, 2, v3
	v_and_b32_e32 v3, -4, v3
	v_lshl_add_u64 v[18:19], v[18:19], 2, v[6:7]
	global_store_dword v[16:17], v14, off sc1
	global_store_dword v[18:19], v15, off sc1
	v_ashrrev_i32_e32 v20, 2, v13
	v_add_u32_e32 v3, v5, v3
	v_and_b32_e32 v13, -4, v13
	v_add_u32_e32 v13, v5, v13
	ds_read2st64_b32 v[14:15], v3 offset1:4
	ds_read2st64_b32 v[16:17], v13 offset1:4
	v_add_u32_e32 v3, 0x800, v8
	v_add_u32_e32 v13, 0x800, v9
	v_cmp_eq_u32_e32 vcc, 0, v12
	s_waitcnt lgkmcnt(1)
	v_mov_b32_e32 v18, v14
	s_waitcnt lgkmcnt(0)
	v_mov_b32_e32 v19, v16
	v_mov_b32_e32 v16, v15
	v_pk_add_f32 v[14:15], v[18:19], v[16:17]
	v_add_u32_e32 v16, s4, v21
	v_add_u32_e32 v18, s4, v20
	v_ashrrev_i32_e32 v17, 31, v16
	v_ashrrev_i32_e32 v19, 31, v18
	v_lshl_add_u64 v[16:17], v[16:17], 2, v[6:7]
	v_ashrrev_i32_e32 v21, 2, v3
	v_and_b32_e32 v3, -4, v3
	v_lshl_add_u64 v[18:19], v[18:19], 2, v[6:7]
	global_store_dword v[16:17], v14, off sc1
	global_store_dword v[18:19], v15, off sc1
	v_ashrrev_i32_e32 v20, 2, v13
	v_add_u32_e32 v3, v5, v3
	v_and_b32_e32 v13, -4, v13
	v_add_u32_e32 v13, v5, v13
	ds_read2st64_b32 v[14:15], v3 offset1:4
	ds_read2st64_b32 v[16:17], v13 offset1:4
	v_add_u32_e32 v3, 0xc00, v8
	v_add_u32_e32 v13, 0xc00, v9
	v_add_u32_e32 v9, 0x1000, v9
	s_waitcnt lgkmcnt(1)
	v_mov_b32_e32 v18, v14
	s_waitcnt lgkmcnt(0)
	v_mov_b32_e32 v19, v16
	v_mov_b32_e32 v16, v15
	v_pk_add_f32 v[14:15], v[18:19], v[16:17]
	v_add_u32_e32 v16, s4, v21
	v_add_u32_e32 v18, s4, v20
	v_ashrrev_i32_e32 v17, 31, v16
	v_ashrrev_i32_e32 v19, 31, v18
	v_lshl_add_u64 v[16:17], v[16:17], 2, v[6:7]
	v_ashrrev_i32_e32 v21, 2, v3
	v_and_b32_e32 v3, -4, v3
	v_lshl_add_u64 v[18:19], v[18:19], 2, v[6:7]
	global_store_dword v[16:17], v14, off sc1
	global_store_dword v[18:19], v15, off sc1
	v_ashrrev_i32_e32 v20, 2, v13
	v_add_u32_e32 v3, v5, v3
	v_and_b32_e32 v13, -4, v13
	v_add_u32_e32 v13, v5, v13
	ds_read2st64_b32 v[14:15], v3 offset1:4
	ds_read2st64_b32 v[16:17], v13 offset1:4
	v_add_u32_e32 v8, 0x1000, v8
	s_or_b64 s[10:11], vcc, s[10:11]
	s_waitcnt lgkmcnt(1)
	v_mov_b32_e32 v18, v14
	s_waitcnt lgkmcnt(0)
	v_mov_b32_e32 v19, v16
	v_mov_b32_e32 v16, v15
	v_pk_add_f32 v[14:15], v[18:19], v[16:17]
	v_add_u32_e32 v16, s4, v21
	v_add_u32_e32 v18, s4, v20
	v_ashrrev_i32_e32 v17, 31, v16
	v_ashrrev_i32_e32 v19, 31, v18
	v_lshl_add_u64 v[16:17], v[16:17], 2, v[6:7]
	v_lshl_add_u64 v[18:19], v[18:19], 2, v[6:7]
	global_store_dword v[16:17], v14, off sc1
	global_store_dword v[18:19], v15, off sc1
	s_andn2_b64 exec, exec, s[10:11]
	s_cbranch_execnz .LBB0_434
	s_or_b64 exec, exec, s[10:11]

.LBB0_438:
	v_and_b32_e32 v12, -4, v8
	v_and_b32_e32 v13, -4, v9
	v_add_u32_e32 v12, v5, v12
	v_add_u32_e32 v14, v5, v13
	ds_read2st64_b32 v[12:13], v12 offset1:4
	ds_read2st64_b32 v[14:15], v14 offset1:4
	v_ashrrev_i32_e32 v18, 2, v8
	v_ashrrev_i32_e32 v11, 2, v9
	v_add_u32_e32 v3, -1, v3
	s_waitcnt lgkmcnt(1)
	v_mov_b32_e32 v16, v12
	s_waitcnt lgkmcnt(0)
	v_mov_b32_e32 v17, v14
	v_mov_b32_e32 v14, v13
	v_pk_add_f32 v[12:13], v[16:17], v[14:15]
	v_add_u32_e32 v14, s4, v18
	v_add_u32_e32 v16, s4, v11
	v_ashrrev_i32_e32 v15, 31, v14
	v_cmp_eq_u32_e32 vcc, 0, v3
	v_ashrrev_i32_e32 v17, 31, v16
	v_lshl_add_u64 v[14:15], v[14:15], 2, v[6:7]
	v_add_u32_e32 v9, 0x400, v9
	v_add_u32_e32 v8, 0x400, v8
	s_or_b64 s[10:11], vcc, s[10:11]
	v_lshl_add_u64 v[16:17], v[16:17], 2, v[6:7]
	global_store_dword v[14:15], v12, off sc1
	global_store_dword v[16:17], v13, off sc1
	s_andn2_b64 exec, exec, s[10:11]
	s_cbranch_execnz .LBB0_438

.LBB0_442:
	v_and_b32_e32 v8, -4, v2
	v_add_u32_e32 v8, v5, v8
	ds_read2st64_b32 v[8:9], v8 offset1:4
	v_ashrrev_i32_e32 v3, 2, v2
	v_cmp_lt_i32_e32 vcc, s12, v2
	s_or_b64 s[6:7], vcc, s[6:7]
	s_waitcnt lgkmcnt(0)
	v_add_f32_e32 v10, v8, v9
	v_add_u32_e32 v8, s4, v3
	v_ashrrev_i32_e32 v9, 31, v8
	v_add_u32_e32 v3, 0x200, v2
	v_lshl_add_u64 v[8:9], v[8:9], 2, v[6:7]
	v_mov_b32_e32 v2, v3
	global_store_dword v[8:9], v10, off sc1
	s_andn2_b64 exec, exec, s[6:7]
	s_cbranch_execnz .LBB0_442

.LBB0_461:
	s_andn2_saveexec_b64 s[4:5], s[4:5]
	s_cbranch_execz .LBB0_481
	s_mov_b64 s[4:5], exec
	s_waitcnt lgkmcnt(0)
	s_waitcnt vmcnt(0)
	v_mbcnt_lo_u32_b32 v3, s4, 0
	v_mbcnt_hi_u32_b32 v3, s5, v3
	v_cmp_eq_u32_e32 vcc, 0, v3
	s_and_saveexec_b64 s[6:7], vcc
	s_cbranch_execz .LBB0_464
	s_bcnt1_i32_b64 s4, s[4:5]
	v_mov_b32_e32 v5, s4
	v_readlane_b32 s4, v253, 9
	v_readlane_b32 s5, v253, 10
	s_nop 4
	global_atomic_add v5, v4, v5, s[4:5] sc0

.LBB0_551:
	s_andn2_saveexec_b64 s[6:7], s[6:7]
	s_cbranch_execz .LBB0_571
	s_mov_b64 s[6:7], exec
	s_waitcnt lgkmcnt(0)
	s_waitcnt vmcnt(0)
	v_mbcnt_lo_u32_b32 v3, s6, 0
	v_mbcnt_hi_u32_b32 v3, s7, v3
	v_cmp_eq_u32_e32 vcc, 0, v3
	s_and_saveexec_b64 s[8:9], vcc
	s_cbranch_execz .LBB0_554
	s_bcnt1_i32_b64 s6, s[6:7]
	v_mov_b32_e32 v5, s6
	v_readlane_b32 s6, v253, 9
	v_readlane_b32 s7, v253, 10
	s_nop 4
	global_atomic_add v5, v4, v5, s[6:7] sc0

.LBB0_574:
	s_add_i32 s15, s13, 0xfffffa00
	s_and_b32 s2, s12, 0x300
	s_lshl_b32 s86, s2, 1
	s_ashr_i32 s2, s15, 2
	s_bfe_u32 s8, s15, 0x80002
	s_and_b32 s2, s2, 0xffffff00
	s_or_b32 s2, s2, s8
	s_ashr_i32 s3, s2, 31
	v_lshl_add_u64 v[6:7], v[10:11], 0, s[86:87]
	s_lshl_b64 s[2:3], s[2:3], 12
	v_lshl_add_u64 v[8:9], v[6:7], 0, s[2:3]
	global_load_dwordx2 v[14:15], v[8:9], off
	s_add_i32 s17, s13, 0xfffffc00
	s_ashr_i32 s3, s17, 2
	s_bfe_u32 s2, s17, 0x80002
	s_and_b32 s3, s3, 0xffffff00
	s_or_b32 s2, s3, s2
	s_ashr_i32 s3, s2, 31
	s_lshl_b64 s[2:3], s[2:3], 12
	s_add_i32 s9, s13, 0xfffffe00
	v_lshl_add_u64 v[8:9], v[6:7], 0, s[2:3]
	s_ashr_i32 s2, s9, 2
	s_and_b32 s2, s2, 0xffffff00
	s_or_b32 s2, s2, s8
	s_ashr_i32 s3, s2, 31
	s_lshl_b64 s[2:3], s[2:3], 12
	global_load_dwordx2 v[12:13], v[8:9], off
	v_lshl_add_u64 v[8:9], v[6:7], 0, s[2:3]
	s_ashr_i32 s3, s13, 2
	s_bfe_u32 s2, s13, 0x80002
	s_and_b32 s3, s3, 0xffffff00
	s_or_b32 s2, s3, s2
	s_ashr_i32 s3, s2, 31
	s_lshl_b64 s[2:3], s[2:3], 12
	v_lshl_add_u64 v[6:7], v[6:7], 0, s[2:3]
	global_load_dwordx2 v[8:9], v[8:9], off
	s_ashr_i32 s8, s15, 10
	global_load_dwordx2 v[6:7], v[6:7], off
	s_waitcnt vmcnt(3)
	v_and_b32_e32 v24, 0xffff0000, v14
	v_lshlrev_b32_e32 v25, 16, v15
	v_and_b32_e32 v15, 0xffff0000, v15
	v_lshlrev_b32_e32 v3, 16, v14
	v_mul_f32_e32 v14, v24, v24
	v_mul_f32_e32 v16, v15, v15
	v_fmac_f32_e32 v14, v3, v3
	v_fmac_f32_e32 v16, v25, v25
	v_add_f32_e32 v14, v14, v16
	s_nop 1
	v_add_f32_dpp v14, v14, v14 row_ror:8 row_mask:0xf bank_mask:0xf bound_ctrl:1
	s_nop 1
	v_add_f32_dpp v14, v14, v14 row_ror:4 row_mask:0xf bank_mask:0xf bound_ctrl:1
	s_nop 1
	v_add_f32_dpp v14, v14, v14 row_ror:2 row_mask:0xf bank_mask:0xf bound_ctrl:1
	s_nop 1
	v_add_f32_dpp v14, v14, v14 row_ror:1 row_mask:0xf bank_mask:0xf bound_ctrl:1
	v_mov_b32_e32 v16, v14
	s_nop 1
	v_permlane16_swap_b32_e32 v14, v16
	v_add_f32_e32 v14, v14, v16
	v_mov_b32_e32 v16, v14
	s_nop 1
	v_permlane32_swap_b32_e32 v14, v16
	v_add_f32_e32 v14, v14, v16
	v_fmamk_f32 v14, v14, 0x3b800000, v236
	v_cmp_gt_f32_e32 vcc, s44, v14
	v_mul_f32_e32 v16, 0x4f800000, v14
	s_nop 0
	v_cndmask_b32_e32 v14, v14, v16, vcc
	v_sqrt_f32_e32 v16, v14
	s_nop 0
	v_add_u32_e32 v17, -1, v16
	v_fma_f32 v18, -v17, v16, v14
	v_cmp_ge_f32_e64 s[2:3], 0, v18
	v_add_u32_e32 v18, 1, v16
	s_nop 0
	v_cndmask_b32_e64 v17, v16, v17, s[2:3]
	v_fma_f32 v16, -v18, v16, v14
	v_cmp_lt_f32_e64 s[2:3], 0, v16
	s_nop 1
	v_cndmask_b32_e64 v16, v17, v18, s[2:3]
	v_mul_f32_e32 v17, 0x37800000, v16
	v_cndmask_b32_e32 v16, v16, v17, vcc
	v_cmp_class_f32_e32 vcc, v14, v237
	s_nop 1
	v_cndmask_b32_e32 v14, v16, v14, vcc
	v_div_scale_f32 v16, s[2:3], v14, v14, 1.0
	v_rcp_f32_e32 v17, v16
	s_mov_b32 s2, 22
	s_ashr_i32 s3, s2, 31
	s_lshl_b64 s[2:3], s[2:3], 3
	v_fma_f32 v18, -v16, v17, 1.0
	s_add_u32 s2, s0, s2
	v_fmac_f32_e32 v17, v18, v17
	v_div_scale_f32 v18, vcc, 1.0, v14, 1.0
	s_addc_u32 s3, s1, s3
	v_mul_f32_e32 v19, v18, v17
	s_load_dwordx2 s[2:3], s[2:3], 0x0
	v_fma_f32 v20, -v16, v19, v18
	v_fmac_f32_e32 v19, v20, v17
	s_lshl_b32 s18, s8, 8
	v_fma_f32 v16, -v16, v19, v18
	s_ashr_i32 s19, s18, 31
	v_div_fmas_f32 v16, v16, v17, v19
	s_lshl_b64 s[18:19], s[18:19], 2
	v_div_fixup_f32 v14, v16, v14, 1.0
	s_waitcnt lgkmcnt(0)
	s_add_u32 s2, s2, s18
	v_mul_f32_e32 v26, 0x3db8aa3b, v14
	s_addc_u32 s3, s3, s19
	v_lshlrev_b32_e32 v14, 2, v2
	global_load_dwordx4 v[16:19], v14, s[2:3]
	s_mov_b32 s2, 21
	s_ashr_i32 s3, s2, 31
	s_lshl_b64 s[2:3], s[2:3], 3
	s_add_u32 s2, s0, s2
	s_addc_u32 s3, s1, s3
	s_load_dwordx2 s[2:3], s[2:3], 0x0
	v_mul_f32_e32 v3, v26, v3
	v_mul_f32_e32 v15, v26, v15
	s_waitcnt lgkmcnt(0)
	s_add_u32 s2, s2, s18
	s_addc_u32 s3, s3, s19
	global_load_dwordx4 v[20:23], v14, s[2:3]
	s_lshl_b32 s2, s8, 2
	s_or_b32 s2, s2, s79
	s_ashr_i32 s3, s2, 31
	s_add_i32 s16, s41, s14
	s_and_b32 s8, s16, 0xff00
	s_lshl_b64 s[2:3], s[2:3], 17
	s_add_u32 s2, s10, s2
	s_addc_u32 s3, s11, s3
	s_lshl_b32 s8, s8, 1
	s_add_u32 s2, s2, s8
	s_addc_u32 s3, s3, 0
	s_ashr_i32 s17, s17, 10
	s_waitcnt vmcnt(1)
	v_mul_f32_e32 v3, v16, v3
	v_mul_f32_e32 v16, v26, v24
	v_mul_f32_e32 v16, v17, v16
	v_mul_f32_e32 v15, v19, v15
	v_lshlrev_b32_e32 v24, 16, v13
	v_and_b32_e32 v13, 0xffff0000, v13
	s_waitcnt vmcnt(0)
	v_mul_f32_e32 v3, v20, v3
	v_mul_f32_e32 v16, v21, v16
	v_cvt_pk_bf16_f32 v16, v3, v16
	v_mul_f32_e32 v3, v26, v25
	v_mul_f32_e32 v3, v18, v3
	v_mul_f32_e32 v3, v22, v3
	v_mul_f32_e32 v15, v23, v15
	v_cvt_pk_bf16_f32 v17, v3, v15
	v_lshlrev_b32_e32 v3, 1, v2
	v_lshlrev_b32_e32 v15, 16, v12
	v_and_b32_e32 v12, 0xffff0000, v12
	global_store_dwordx2 v3, v[16:17], s[2:3] sc1
	v_mul_f32_e32 v16, v12, v12
	v_mul_f32_e32 v17, v13, v13
	v_fmac_f32_e32 v16, v15, v15
	v_fmac_f32_e32 v17, v24, v24
	v_add_f32_e32 v16, v16, v17
	s_nop 1
	v_add_f32_dpp v16, v16, v16 row_ror:8 row_mask:0xf bank_mask:0xf bound_ctrl:1
	s_nop 1
	v_add_f32_dpp v16, v16, v16 row_ror:4 row_mask:0xf bank_mask:0xf bound_ctrl:1
	s_nop 1
	v_add_f32_dpp v16, v16, v16 row_ror:2 row_mask:0xf bank_mask:0xf bound_ctrl:1
	s_nop 1
	v_add_f32_dpp v16, v16, v16 row_ror:1 row_mask:0xf bank_mask:0xf bound_ctrl:1
	v_mov_b32_e32 v17, v16
	s_nop 1
	v_permlane16_swap_b32_e32 v16, v17
	v_add_f32_e32 v16, v16, v17
	v_mov_b32_e32 v17, v16
	s_nop 1
	v_permlane32_swap_b32_e32 v16, v17
	v_add_f32_e32 v16, v16, v17
	v_fmamk_f32 v16, v16, 0x3b800000, v236
	v_cmp_gt_f32_e32 vcc, s44, v16
	v_mul_f32_e32 v17, 0x4f800000, v16
	s_nop 0
	v_cndmask_b32_e32 v16, v16, v17, vcc
	v_sqrt_f32_e32 v17, v16
	s_nop 0
	v_add_u32_e32 v18, -1, v17
	v_fma_f32 v19, -v18, v17, v16
	v_cmp_ge_f32_e64 s[2:3], 0, v19
	v_add_u32_e32 v19, 1, v17
	s_nop 0
	v_cndmask_b32_e64 v18, v17, v18, s[2:3]
	v_fma_f32 v17, -v19, v17, v16
	v_cmp_lt_f32_e64 s[2:3], 0, v17
	s_nop 1
	v_cndmask_b32_e64 v17, v18, v19, s[2:3]
	v_mul_f32_e32 v18, 0x37800000, v17
	v_cndmask_b32_e32 v17, v17, v18, vcc
	v_cmp_class_f32_e32 vcc, v16, v237
	s_nop 1
	v_cndmask_b32_e32 v16, v17, v16, vcc
	v_div_scale_f32 v17, s[2:3], v16, v16, 1.0
	v_rcp_f32_e32 v18, v17
	s_mov_b32 s2, 22
	s_ashr_i32 s3, s2, 31
	s_lshl_b64 s[2:3], s[2:3], 3
	s_add_u32 s2, s0, s2
	v_fma_f32 v19, -v17, v18, 1.0
	s_addc_u32 s3, s1, s3
	v_fmac_f32_e32 v18, v19, v18
	v_div_scale_f32 v19, vcc, 1.0, v16, 1.0
	s_load_dwordx2 s[2:3], s[2:3], 0x0
	v_mul_f32_e32 v20, v19, v18
	v_fma_f32 v21, -v17, v20, v19
	s_lshl_b32 s18, s17, 8
	v_fmac_f32_e32 v20, v21, v18
	s_ashr_i32 s19, s18, 31
	v_fma_f32 v17, -v17, v20, v19
	s_lshl_b64 s[18:19], s[18:19], 2
	v_div_fmas_f32 v17, v17, v18, v20
	s_waitcnt lgkmcnt(0)
	s_add_u32 s2, s2, s18
	v_div_fixup_f32 v16, v17, v16, 1.0
	s_addc_u32 s3, s3, s19
	v_mul_f32_e32 v25, 0x3db8aa3b, v16
	global_load_dwordx4 v[16:19], v14, s[2:3]
	s_mov_b32 s2, 21
	s_ashr_i32 s3, s2, 31
	s_lshl_b64 s[2:3], s[2:3], 3
	s_add_u32 s2, s0, s2
	s_addc_u32 s3, s1, s3
	s_load_dwordx2 s[2:3], s[2:3], 0x0
	v_mul_f32_e32 v15, v25, v15
	v_mul_f32_e32 v12, v25, v12
	v_mul_f32_e32 v13, v25, v13
	s_waitcnt lgkmcnt(0)
	s_add_u32 s2, s2, s18
	s_addc_u32 s3, s3, s19
	global_load_dwordx4 v[20:23], v14, s[2:3]
	s_lshl_b32 s2, s17, 2
	s_or_b32 s2, s2, s79
	s_ashr_i32 s3, s2, 31
	s_add_i32 s17, s16, 0x8000
	s_and_b32 s17, s17, 0xff00
	s_lshl_b64 s[2:3], s[2:3], 17
	s_add_u32 s2, s10, s2
	s_addc_u32 s3, s11, s3
	s_lshl_b32 s17, s17, 1
	s_add_u32 s2, s2, s17
	s_addc_u32 s3, s3, 0
	s_ashr_i32 s9, s9, 10
	s_waitcnt vmcnt(1)
	v_mul_f32_e32 v15, v16, v15
	v_mul_f32_e32 v12, v17, v12
	v_mul_f32_e32 v13, v19, v13
	s_waitcnt vmcnt(0)
	v_mul_f32_e32 v15, v20, v15
	v_mul_f32_e32 v12, v21, v12
	v_cvt_pk_bf16_f32 v12, v15, v12
	v_mul_f32_e32 v15, v25, v24
	v_mul_f32_e32 v15, v18, v15
	v_mul_f32_e32 v13, v23, v13
	v_mul_f32_e32 v15, v22, v15
	v_cvt_pk_bf16_f32 v13, v15, v13
	global_store_dwordx2 v3, v[12:13], s[2:3] sc1
	v_lshlrev_b32_e32 v12, 16, v8
	v_and_b32_e32 v8, 0xffff0000, v8
	v_lshlrev_b32_e32 v13, 16, v9
	v_and_b32_e32 v9, 0xffff0000, v9
	v_mul_f32_e32 v15, v8, v8
	v_mul_f32_e32 v16, v9, v9
	v_fmac_f32_e32 v15, v12, v12
	v_fmac_f32_e32 v16, v13, v13
	v_add_f32_e32 v15, v15, v16
	s_nop 1
	v_add_f32_dpp v15, v15, v15 row_ror:8 row_mask:0xf bank_mask:0xf bound_ctrl:1
	s_nop 1
	v_add_f32_dpp v15, v15, v15 row_ror:4 row_mask:0xf bank_mask:0xf bound_ctrl:1
	s_nop 1
	v_add_f32_dpp v15, v15, v15 row_ror:2 row_mask:0xf bank_mask:0xf bound_ctrl:1
	s_nop 1
	v_add_f32_dpp v15, v15, v15 row_ror:1 row_mask:0xf bank_mask:0xf bound_ctrl:1
	v_mov_b32_e32 v16, v15
	s_nop 1
	v_permlane16_swap_b32_e32 v15, v16
	v_add_f32_e32 v15, v15, v16
	v_mov_b32_e32 v16, v15
	s_nop 1
	v_permlane32_swap_b32_e32 v15, v16
	v_add_f32_e32 v15, v15, v16
	v_fmamk_f32 v15, v15, 0x3b800000, v236
	v_cmp_gt_f32_e32 vcc, s44, v15
	v_mul_f32_e32 v16, 0x4f800000, v15
	s_nop 0
	v_cndmask_b32_e32 v15, v15, v16, vcc
	v_sqrt_f32_e32 v16, v15
	s_nop 0
	v_add_u32_e32 v17, -1, v16
	v_fma_f32 v18, -v17, v16, v15
	v_cmp_ge_f32_e64 s[2:3], 0, v18
	v_add_u32_e32 v18, 1, v16
	s_nop 0
	v_cndmask_b32_e64 v17, v16, v17, s[2:3]
	v_fma_f32 v16, -v18, v16, v15
	v_cmp_lt_f32_e64 s[2:3], 0, v16
	s_nop 1
	v_cndmask_b32_e64 v16, v17, v18, s[2:3]
	v_mul_f32_e32 v17, 0x37800000, v16
	v_cndmask_b32_e32 v16, v16, v17, vcc
	v_cmp_class_f32_e32 vcc, v15, v237
	s_nop 1
	v_cndmask_b32_e32 v15, v16, v15, vcc
	v_div_scale_f32 v16, s[2:3], v15, v15, 1.0
	s_mov_b32 s2, 22
	v_rcp_f32_e32 v17, v16
	s_ashr_i32 s3, s2, 31
	s_lshl_b64 s[2:3], s[2:3], 3
	s_add_u32 s2, s0, s2
	s_addc_u32 s3, s1, s3
	v_fma_f32 v18, -v16, v17, 1.0
	s_load_dwordx2 s[2:3], s[2:3], 0x0
	v_fmac_f32_e32 v17, v18, v17
	v_div_scale_f32 v18, vcc, 1.0, v15, 1.0
	v_mul_f32_e32 v19, v18, v17
	s_lshl_b32 s18, s9, 8
	v_fma_f32 v20, -v16, v19, v18
	s_ashr_i32 s19, s18, 31
	v_fmac_f32_e32 v19, v20, v17
	s_lshl_b64 s[18:19], s[18:19], 2
	v_fma_f32 v16, -v16, v19, v18
	s_waitcnt lgkmcnt(0)
	s_add_u32 s2, s2, s18
	v_div_fmas_f32 v16, v16, v17, v19
	s_addc_u32 s3, s3, s19
	v_div_fixup_f32 v15, v16, v15, 1.0
	global_load_dwordx4 v[16:19], v14, s[2:3]
	s_mov_b32 s2, 21
	s_ashr_i32 s3, s2, 31
	s_lshl_b64 s[2:3], s[2:3], 3
	s_add_u32 s2, s0, s2
	s_addc_u32 s3, s1, s3
	s_load_dwordx2 s[2:3], s[2:3], 0x0
	v_mul_f32_e32 v15, 0x3db8aa3b, v15
	v_mul_f32_e32 v12, v15, v12
	v_mul_f32_e32 v8, v15, v8
	v_mul_f32_e32 v9, v15, v9
	s_waitcnt lgkmcnt(0)
	s_add_u32 s2, s2, s18
	s_addc_u32 s3, s3, s19
	global_load_dwordx4 v[20:23], v14, s[2:3]
	s_lshl_b32 s2, s9, 2
	s_or_b32 s2, s2, s79
	s_ashr_i32 s3, s2, 31
	s_lshl_b64 s[2:3], s[2:3], 17
	s_add_u32 s2, s10, s2
	s_addc_u32 s3, s11, s3
	s_add_u32 s2, s2, s8
	s_addc_u32 s3, s3, 0
	s_ashr_i32 s17, s13, 10
	s_waitcnt vmcnt(1)
	v_mul_f32_e32 v12, v16, v12
	v_mul_f32_e32 v8, v17, v8
	v_mul_f32_e32 v9, v19, v9
	v_lshlrev_b32_e32 v16, 16, v6
	s_waitcnt vmcnt(0)
	v_mul_f32_e32 v12, v20, v12
	v_mul_f32_e32 v8, v21, v8
	v_cvt_pk_bf16_f32 v8, v12, v8
	v_mul_f32_e32 v12, v15, v13
	v_mul_f32_e32 v12, v18, v12
	v_mul_f32_e32 v12, v22, v12
	v_mul_f32_e32 v9, v23, v9
	v_cvt_pk_bf16_f32 v9, v12, v9
	v_and_b32_e32 v15, 0xffff0000, v6
	v_and_b32_e32 v12, 0xffff0000, v7
	v_lshlrev_b32_e32 v13, 16, v7
	v_mul_f32_e32 v6, v15, v15
	v_mul_f32_e32 v7, v12, v12
	v_fmac_f32_e32 v6, v16, v16
	v_fmac_f32_e32 v7, v13, v13
	v_add_f32_e32 v6, v6, v7
	global_store_dwordx2 v3, v[8:9], s[2:3] sc1
	s_nop 0
	v_add_f32_dpp v6, v6, v6 row_ror:8 row_mask:0xf bank_mask:0xf bound_ctrl:1
	s_nop 1
	v_add_f32_dpp v6, v6, v6 row_ror:4 row_mask:0xf bank_mask:0xf bound_ctrl:1
	s_nop 1
	v_add_f32_dpp v6, v6, v6 row_ror:2 row_mask:0xf bank_mask:0xf bound_ctrl:1
	s_nop 1
	v_add_f32_dpp v6, v6, v6 row_ror:1 row_mask:0xf bank_mask:0xf bound_ctrl:1
	v_mov_b32_e32 v7, v6
	s_nop 1
	v_permlane16_swap_b32_e32 v6, v7
	v_add_f32_e32 v6, v6, v7
	v_mov_b32_e32 v7, v6
	s_nop 1
	v_permlane32_swap_b32_e32 v6, v7
	v_add_f32_e32 v6, v6, v7
	v_fmamk_f32 v6, v6, 0x3b800000, v236
	v_cmp_gt_f32_e32 vcc, s44, v6
	v_mul_f32_e32 v7, 0x4f800000, v6
	s_nop 0
	v_cndmask_b32_e32 v6, v6, v7, vcc
	v_sqrt_f32_e32 v7, v6
	s_nop 0
	v_add_u32_e32 v8, -1, v7
	v_fma_f32 v9, -v8, v7, v6
	v_cmp_ge_f32_e64 s[2:3], 0, v9
	v_add_u32_e32 v9, 1, v7
	s_nop 0
	v_cndmask_b32_e64 v8, v7, v8, s[2:3]
	v_fma_f32 v7, -v9, v7, v6
	v_cmp_lt_f32_e64 s[2:3], 0, v7
	s_nop 1
	v_cndmask_b32_e64 v7, v8, v9, s[2:3]
	v_mul_f32_e32 v8, 0x37800000, v7
	v_cndmask_b32_e32 v7, v7, v8, vcc
	v_cmp_class_f32_e32 vcc, v6, v237
	s_nop 1
	v_cndmask_b32_e32 v6, v7, v6, vcc
	v_div_scale_f32 v7, s[2:3], v6, v6, 1.0
	v_rcp_f32_e32 v8, v7
	s_mov_b32 s2, 22
	s_ashr_i32 s3, s2, 31
	s_lshl_b64 s[2:3], s[2:3], 3
	s_add_u32 s2, s0, s2
	v_fma_f32 v9, -v7, v8, 1.0
	s_addc_u32 s3, s1, s3
	v_fmac_f32_e32 v8, v9, v8
	v_div_scale_f32 v9, vcc, 1.0, v6, 1.0
	s_load_dwordx2 s[8:9], s[2:3], 0x0
	v_mul_f32_e32 v17, v9, v8
	v_fma_f32 v18, -v7, v17, v9
	s_lshl_b32 s2, s17, 8
	v_fmac_f32_e32 v17, v18, v8
	s_ashr_i32 s3, s2, 31
	v_fma_f32 v7, -v7, v17, v9
	s_lshl_b64 s[2:3], s[2:3], 2
	v_div_fmas_f32 v7, v7, v8, v17
	s_waitcnt lgkmcnt(0)
	s_add_u32 s8, s8, s2
	v_div_fixup_f32 v6, v7, v6, 1.0
	s_addc_u32 s9, s9, s3
	v_mul_f32_e32 v17, 0x3db8aa3b, v6
	global_load_dwordx4 v[6:9], v14, s[8:9]
	s_mov_b32 s8, 21
	s_ashr_i32 s9, s8, 31
	s_lshl_b64 s[8:9], s[8:9], 3
	s_add_u32 s8, s0, s8
	s_addc_u32 s9, s1, s9
	s_load_dwordx2 s[8:9], s[8:9], 0x0
	s_waitcnt lgkmcnt(0)
	s_add_u32 s2, s8, s2
	s_addc_u32 s3, s9, s3
	global_load_dwordx4 v[18:21], v14, s[2:3]
	s_lshl_b32 s2, s17, 2
	s_or_b32 s2, s2, s79
	v_mul_f32_e32 v14, v17, v16
	s_ashr_i32 s3, s2, 31
	s_add_i32 s16, s16, 0x18000
	s_and_b32 s8, s16, 0xff00
	s_lshl_b64 s[2:3], s[2:3], 17
	s_add_u32 s2, s10, s2
	s_addc_u32 s3, s11, s3
	s_lshl_b32 s8, s8, 1
	s_add_u32 s2, s2, s8
	s_addc_u32 s3, s3, 0
	s_add_i32 s14, s14, 0x20000
	s_addk_i32 s13, 0x800
	s_add_i32 s12, s12, 0x80000
	s_cmpk_lt_i32 s15, 0x800
	s_waitcnt vmcnt(1)
	v_mul_f32_e32 v6, v6, v14
	v_mul_f32_e32 v14, v17, v15
	v_mul_f32_e32 v7, v7, v14
	s_waitcnt vmcnt(0)
	v_mul_f32_e32 v6, v18, v6
	v_mul_f32_e32 v7, v19, v7
	v_cvt_pk_bf16_f32 v6, v6, v7
	v_mul_f32_e32 v7, v17, v13
	v_mul_f32_e32 v7, v8, v7
	v_mul_f32_e32 v8, v17, v12
	v_mul_f32_e32 v7, v20, v7
	v_mul_f32_e32 v8, v9, v8
	v_mul_f32_e32 v8, v21, v8
	v_cvt_pk_bf16_f32 v7, v7, v8
	global_store_dwordx2 v3, v[6:7], s[2:3] sc1
	s_cbranch_scc1 .LBB0_574

.LBB0_577:
	s_ashr_i32 s12, s11, 1
	s_and_b32 s12, s12, 0xffffff00
	s_and_b32 s15, s8, 0xc0
	v_or_b32_e32 v2, s12, v5
	v_or_b32_e32 v2, s15, v2
	v_ashrrev_i32_e32 v3, 31, v2
	s_and_b32 s2, s8, 0x300
	v_lshlrev_b64 v[2:3], 12, v[2:3]
	s_and_b32 s3, s9, 0xf8
	v_lshl_add_u64 v[2:3], s[4:5], 0, v[2:3]
	s_lshl_b32 s86, s2, 1
	v_lshl_add_u64 v[2:3], v[2:3], 0, s[86:87]
	s_lshl_b32 s2, s3, 1
	s_mov_b32 s3, s87
	v_lshl_add_u64 v[10:11], v[2:3], 0, s[2:3]
	global_load_dwordx4 v[14:17], v[10:11], off offset:2048
	s_add_i32 s14, s11, 0x200
	s_ashr_i32 s12, s14, 1
	s_and_b32 s12, s12, 0xffffff00
	v_or_b32_e32 v2, s12, v5
	v_or_b32_e32 v2, s15, v2
	v_ashrrev_i32_e32 v3, 31, v2
	v_lshlrev_b64 v[2:3], 12, v[2:3]
	s_add_i32 s13, s11, 0x400
	v_lshl_add_u64 v[2:3], s[4:5], 0, v[2:3]
	s_ashr_i32 s12, s13, 1
	v_lshl_add_u64 v[2:3], v[2:3], 0, s[86:87]
	s_and_b32 s12, s12, 0xffffff00
	v_lshl_add_u64 v[6:7], v[2:3], 0, s[2:3]
	v_or_b32_e32 v2, s12, v5
	s_add_i32 s12, s11, 0x600
	s_ashr_i32 s16, s12, 1
	s_and_b32 s16, s16, 0xffffff00
	v_or_b32_e32 v8, s16, v5
	v_or_b32_e32 v2, s15, v2
	v_or_b32_e32 v8, s15, v8
	v_ashrrev_i32_e32 v3, 31, v2
	v_ashrrev_i32_e32 v9, 31, v8
	v_lshlrev_b64 v[2:3], 12, v[2:3]
	v_lshlrev_b64 v[8:9], 12, v[8:9]
	v_lshl_add_u64 v[2:3], s[4:5], 0, v[2:3]
	v_lshl_add_u64 v[8:9], s[4:5], 0, v[8:9]
	v_lshl_add_u64 v[2:3], v[2:3], 0, s[86:87]
	v_lshl_add_u64 v[8:9], v[8:9], 0, s[86:87]
	v_lshl_add_u64 v[2:3], v[2:3], 0, s[2:3]
	v_lshl_add_u64 v[12:13], v[8:9], 0, s[2:3]
	s_and_b32 s3, s10, 0xf800
	s_bfe_u32 s2, s11, 0x20007
	s_lshl_b32 s3, s3, 1
	s_add_u32 s16, s6, s3
	v_or_b32_e32 v8, s15, v5
	s_addc_u32 s17, s7, 0
	s_ashr_i32 s3, s11, 7
	v_lshlrev_b32_e32 v8, 1, v8
	v_mov_b32_e32 v9, v4
	s_and_b32 s3, s3, -4
	v_lshl_add_u64 v[8:9], s[16:17], 0, v[8:9]
	s_or_b32 s16, s3, s2
	s_ashr_i32 s17, s16, 31
	s_lshl_b64 s[16:17], s[16:17], 17
	v_lshl_add_u64 v[18:19], v[8:9], 0, s[16:17]
	s_ashr_i32 s3, s14, 7
	s_and_b32 s3, s3, -4
	s_or_b32 s14, s3, s2
	s_ashr_i32 s15, s14, 31
	s_lshl_b64 s[14:15], s[14:15], 17
	v_lshl_add_u64 v[10:11], v[8:9], 0, s[14:15]
	s_ashr_i32 s3, s13, 7
	s_and_b32 s3, s3, -4
	s_or_b32 s14, s3, s2
	s_ashr_i32 s15, s14, 31
	s_lshl_b64 s[14:15], s[14:15], 17
	s_ashr_i32 s3, s12, 7
	s_and_b32 s3, s3, -4
	s_or_b32 s2, s3, s2
	s_ashr_i32 s3, s2, 31
	s_lshl_b64 s[2:3], s[2:3], 17
	s_add_i32 s10, s10, 0x400000
	s_addk_i32 s9, 0x4000
	s_addk_i32 s8, 0x1000
	s_waitcnt vmcnt(0)
	global_store_short v[18:19], v14, off sc1
	global_store_short_d16_hi v[18:19], v14, off offset:512 sc1
	global_store_short v[18:19], v15, off offset:1024 sc1
	global_store_short_d16_hi v[18:19], v15, off offset:1536 sc1
	global_store_short v[18:19], v16, off offset:2048 sc1
	global_store_short_d16_hi v[18:19], v16, off offset:2560 sc1
	global_store_short v[18:19], v17, off offset:3072 sc1
	global_store_short_d16_hi v[18:19], v17, off offset:3584 sc1
	global_load_dwordx4 v[14:17], v[6:7], off offset:2048
	v_lshl_add_u64 v[6:7], v[8:9], 0, s[14:15]
	s_waitcnt vmcnt(0)
	global_store_short v[10:11], v14, off sc1
	global_store_short_d16_hi v[10:11], v14, off offset:512 sc1
	global_store_short v[10:11], v15, off offset:1024 sc1
	global_store_short_d16_hi v[10:11], v15, off offset:1536 sc1
	global_store_short v[10:11], v16, off offset:2048 sc1
	global_store_short_d16_hi v[10:11], v16, off offset:2560 sc1
	global_store_short v[10:11], v17, off offset:3072 sc1
	global_store_short_d16_hi v[10:11], v17, off offset:3584 sc1
	global_load_dwordx4 v[14:17], v[2:3], off offset:2048
	v_lshl_add_u64 v[2:3], v[8:9], 0, s[2:3]
	s_add_i32 s2, s11, 0x800
	s_cmp_gt_i32 s11, -1
	s_mov_b32 s11, s2
	s_waitcnt vmcnt(0)
	global_store_short v[6:7], v14, off sc1
	global_store_short_d16_hi v[6:7], v14, off offset:512 sc1
	global_store_short v[6:7], v15, off offset:1024 sc1
	global_store_short_d16_hi v[6:7], v15, off offset:1536 sc1
	global_store_short v[6:7], v16, off offset:2048 sc1
	global_load_dwordx4 v[10:13], v[12:13], off offset:2048
	s_nop 0
	global_store_short_d16_hi v[6:7], v16, off offset:2560 sc1
	global_store_short v[6:7], v17, off offset:3072 sc1
	global_store_short_d16_hi v[6:7], v17, off offset:3584 sc1
	s_waitcnt vmcnt(3)
	global_store_short v[2:3], v10, off sc1
	global_store_short_d16_hi v[2:3], v10, off offset:512 sc1
	global_store_short v[2:3], v11, off offset:1024 sc1
	global_store_short_d16_hi v[2:3], v11, off offset:1536 sc1
	global_store_short v[2:3], v12, off offset:2048 sc1
	global_store_short_d16_hi v[2:3], v12, off offset:2560 sc1
	global_store_short v[2:3], v13, off offset:3072 sc1
	global_store_short_d16_hi v[2:3], v13, off offset:3584 sc1
	s_cbranch_scc0 .LBB0_577

.LBB0_587:
	v_cvt_pk_bf16_f32 v192, v99, v163
	v_add_u32_e32 v99, s60, v161
	v_and_b32_e32 v99, 0x80, v99
	v_or3_b32 v99, v99, v152, v125
	v_cvt_pk_bf16_f32 v194, v187, v188
	v_lshl_add_u32 v187, v99, 8, s54
	v_lshlrev_b32_e32 v99, 1, v152
	v_cvt_pk_bf16_f32 v193, v165, v169
	v_add_u32_e32 v163, s60, v160
	v_and_b32_e32 v169, 12, v99
	v_and_b32_e32 v163, 0x80, v163
	v_bitop3_b32 v99, v169, v120, v121 bitop3:0x36
	v_or3_b32 v163, v163, v152, v130
	v_lshlrev_b32_e32 v99, 4, v99
	v_lshl_add_u32 v216, v163, 8, s54
	v_add_u32_e32 v163, v187, v99
	v_add_u32_e32 v165, v163, v138
	v_add_u32_e32 v163, v163, v139
	v_cvt_pk_bf16_f32 v195, v189, v190
	ds_read_b64_tr_b16 v[188:189], v165
	ds_read_b64_tr_b16 v[196:197], v163
	v_add_u32_e32 v165, v216, v99
	v_add_u32_e32 v190, v165, v138
	v_add_u32_e32 v163, v165, v139
	ds_read_b64_tr_b16 v[190:191], v190
	ds_read_b64_tr_b16 v[198:199], v163
	v_bitop3_b32 v163, v169, v140, v121 bitop3:0x36
	v_lshlrev_b32_e32 v163, 4, v163
	v_add_u32_e32 v165, v187, v163
	v_add_u32_e32 v200, v165, v138
	v_add_u32_e32 v206, v216, v163
	v_add_u32_e32 v165, v165, v139
	ds_read_b64_tr_b16 v[200:201], v200
	ds_read_b64_tr_b16 v[204:205], v165
	v_add_u32_e32 v202, v206, v138
	v_add_u32_e32 v165, v206, v139
	ds_read_b64_tr_b16 v[202:203], v202
	ds_read_b64_tr_b16 v[206:207], v165
	s_ashr_i32 s53, s52, 31
	v_lshl_add_u64 v[94:95], v[102:103], 0, s[52:53]
	s_setprio 1
	s_waitcnt lgkmcnt(5)
	v_mfma_f32_16x16x32_bf16 v[188:191], v[188:191], v[192:195], 0
	s_waitcnt lgkmcnt(4)
	v_mfma_f32_16x16x32_bf16 v[196:199], v[196:199], v[192:195], 0
	s_waitcnt lgkmcnt(1)
	v_mfma_f32_16x16x32_bf16 v[200:203], v[200:203], v[192:195], 0
	s_waitcnt lgkmcnt(0)
	v_mfma_f32_16x16x32_bf16 v[204:207], v[204:207], v[192:195], 0
	s_setprio 0
	v_bitop3_b32 v165, v169, v141, v121 bitop3:0x36
	v_bitop3_b32 v169, v169, v142, v121 bitop3:0x36
	v_lshlrev_b32_e32 v165, 4, v165
	v_lshlrev_b32_e32 v169, 4, v169
	v_add_u32_e32 v208, v187, v165
	v_add_u32_e32 v210, v216, v165
	v_add_u32_e32 v187, v187, v169
	v_add_u32_e32 v216, v216, v169
	v_add_u32_e32 v209, v208, v138
	v_add_u32_e32 v211, v210, v138
	v_add_u32_e32 v212, v208, v139
	v_add_u32_e32 v214, v210, v139
	v_add_u32_e32 v217, v187, v138
	v_add_u32_e32 v218, v216, v138
	v_add_u32_e32 v222, v216, v139
	ds_read_b64_tr_b16 v[208:209], v209
	ds_read_b64_tr_b16 v[210:211], v211
	ds_read_b64_tr_b16 v[212:213], v212
	ds_read_b64_tr_b16 v[214:215], v214
	v_add_u32_e32 v187, v187, v139
	ds_read_b64_tr_b16 v[216:217], v217
	ds_read_b64_tr_b16 v[218:219], v218
	ds_read_b64_tr_b16 v[220:221], v187
	ds_read_b64_tr_b16 v[222:223], v222
	s_setprio 1
	s_waitcnt lgkmcnt(6)
	v_mfma_f32_16x16x32_bf16 v[208:211], v[208:211], v[192:195], 0
	s_waitcnt lgkmcnt(4)
	v_mfma_f32_16x16x32_bf16 v[212:215], v[212:215], v[192:195], 0
	s_waitcnt lgkmcnt(2)
	v_mfma_f32_16x16x32_bf16 v[216:219], v[216:219], v[192:195], 0
	s_waitcnt lgkmcnt(0)
	v_mfma_f32_16x16x32_bf16 v[192:195], v[220:223], v[192:195], 0
	s_setprio 0
	v_cvt_pk_bf16_f32 v180, v179, v180
	v_cvt_pk_bf16_f32 v181, v181, v182
	v_cvt_pk_bf16_f32 v182, v183, v184
	v_add_u32_e32 v179, s60, v159
	v_add_u32_e32 v184, s60, v158
	v_and_b32_e32 v179, 0x80, v179
	v_and_b32_e32 v184, 0x80, v184
	v_or3_b32 v179, v179, v152, v131
	v_or3_b32 v184, v184, v152, v132
	v_lshl_add_u32 v179, v179, 8, s54
	v_lshl_add_u32 v232, v184, 8, s54
	v_add_u32_e32 v220, v179, v99
	v_add_u32_e32 v222, v232, v99
	v_add_u32_e32 v228, v179, v163
	v_add_u32_e32 v230, v232, v163
	v_cvt_pk_bf16_f32 v183, v185, v186
	v_add_u32_e32 v184, v220, v138
	v_add_u32_e32 v186, v222, v138
	v_add_u32_e32 v220, v220, v139
	v_add_u32_e32 v222, v222, v139
	v_add_u32_e32 v224, v228, v138
	v_add_u32_e32 v226, v230, v138
	v_add_u32_e32 v228, v228, v139
	v_add_u32_e32 v230, v230, v139
	ds_read_b64_tr_b16 v[184:185], v184
	ds_read_b64_tr_b16 v[186:187], v186
	ds_read_b64_tr_b16 v[220:221], v220
	ds_read_b64_tr_b16 v[222:223], v222
	ds_read_b64_tr_b16 v[224:225], v224
	ds_read_b64_tr_b16 v[226:227], v226
	ds_read_b64_tr_b16 v[228:229], v228
	ds_read_b64_tr_b16 v[230:231], v230
	s_setprio 1
	s_waitcnt lgkmcnt(6)
	v_mfma_f32_16x16x32_bf16 v[184:187], v[184:187], v[180:183], v[188:191]
	s_waitcnt lgkmcnt(4)
	v_mfma_f32_16x16x32_bf16 v[188:191], v[220:223], v[180:183], v[196:199]
	s_waitcnt lgkmcnt(2)
	v_mfma_f32_16x16x32_bf16 v[196:199], v[224:227], v[180:183], v[200:203]
	s_waitcnt lgkmcnt(0)
	v_mfma_f32_16x16x32_bf16 v[200:203], v[228:231], v[180:183], v[204:207]
	s_setprio 0
	s_nop 1
	v_add_u32_e32 v204, v179, v165
	v_add_u32_e32 v206, v232, v165
	v_add_u32_e32 v179, v179, v169
	v_add_u32_e32 v225, v232, v169
	v_add_u32_e32 v205, v204, v138
	v_add_u32_e32 v207, v206, v138
	v_add_u32_e32 v220, v204, v139
	v_add_u32_e32 v222, v206, v139
	v_add_u32_e32 v224, v179, v138
	v_add_u32_e32 v226, v225, v138
	v_add_u32_e32 v230, v225, v139
	ds_read_b64_tr_b16 v[204:205], v205
	ds_read_b64_tr_b16 v[206:207], v207
	ds_read_b64_tr_b16 v[220:221], v220
	ds_read_b64_tr_b16 v[222:223], v222
	v_add_u32_e32 v179, v179, v139
	ds_read_b64_tr_b16 v[224:225], v224
	ds_read_b64_tr_b16 v[226:227], v226
	ds_read_b64_tr_b16 v[228:229], v179
	ds_read_b64_tr_b16 v[230:231], v230
	s_setprio 1
	s_waitcnt lgkmcnt(6)
	v_mfma_f32_16x16x32_bf16 v[204:207], v[204:207], v[180:183], v[208:211]
	s_waitcnt lgkmcnt(4)
	v_mfma_f32_16x16x32_bf16 v[208:211], v[220:223], v[180:183], v[212:215]
	s_waitcnt lgkmcnt(2)
	v_mfma_f32_16x16x32_bf16 v[212:215], v[224:227], v[180:183], v[216:219]
	s_waitcnt lgkmcnt(0)
	v_mfma_f32_16x16x32_bf16 v[180:183], v[228:231], v[180:183], v[192:195]
	s_setprio 0
	v_cvt_pk_bf16_f32 v172, v171, v172
	v_cvt_pk_bf16_f32 v173, v173, v174
	v_cvt_pk_bf16_f32 v174, v175, v176
	v_add_u32_e32 v171, s60, v157
	v_add_u32_e32 v176, s60, v156
	v_and_b32_e32 v171, 0x80, v171
	v_and_b32_e32 v176, 0x80, v176
	v_or3_b32 v171, v171, v152, v133
	v_or3_b32 v176, v176, v152, v134
	v_lshl_add_u32 v171, v171, 8, s54
	v_lshl_add_u32 v224, v176, 8, s54
	v_add_u32_e32 v192, v171, v99
	v_add_u32_e32 v194, v224, v99
	v_add_u32_e32 v220, v171, v163
	v_add_u32_e32 v222, v224, v163
	v_cvt_pk_bf16_f32 v175, v177, v178
	v_add_u32_e32 v176, v192, v138
	v_add_u32_e32 v178, v194, v138
	v_add_u32_e32 v192, v192, v139
	v_add_u32_e32 v194, v194, v139
	v_add_u32_e32 v216, v220, v138
	v_add_u32_e32 v218, v222, v138
	v_add_u32_e32 v220, v220, v139
	v_add_u32_e32 v222, v222, v139
	ds_read_b64_tr_b16 v[176:177], v176
	ds_read_b64_tr_b16 v[178:179], v178
	ds_read_b64_tr_b16 v[192:193], v192
	ds_read_b64_tr_b16 v[194:195], v194
	ds_read_b64_tr_b16 v[216:217], v216
	ds_read_b64_tr_b16 v[218:219], v218
	ds_read_b64_tr_b16 v[220:221], v220
	ds_read_b64_tr_b16 v[222:223], v222
	s_setprio 1
	s_waitcnt lgkmcnt(6)
	v_mfma_f32_16x16x32_bf16 v[176:179], v[176:179], v[172:175], v[184:187]
	s_waitcnt lgkmcnt(4)
	v_mfma_f32_16x16x32_bf16 v[184:187], v[192:195], v[172:175], v[188:191]
	s_waitcnt lgkmcnt(2)
	v_mfma_f32_16x16x32_bf16 v[188:191], v[216:219], v[172:175], v[196:199]
	s_waitcnt lgkmcnt(0)
	v_mfma_f32_16x16x32_bf16 v[192:195], v[220:223], v[172:175], v[200:203]
	s_setprio 0
	v_add_u32_e32 v196, v171, v165
	v_add_u32_e32 v198, v224, v165
	v_add_u32_e32 v171, v171, v169
	v_add_u32_e32 v217, v224, v169
	v_add_u32_e32 v197, v196, v138
	v_add_u32_e32 v199, v198, v138
	v_add_u32_e32 v200, v196, v139
	v_add_u32_e32 v202, v198, v139
	v_add_u32_e32 v216, v171, v138
	v_add_u32_e32 v218, v217, v138
	v_add_u32_e32 v222, v217, v139
	ds_read_b64_tr_b16 v[196:197], v197
	ds_read_b64_tr_b16 v[198:199], v199
	ds_read_b64_tr_b16 v[200:201], v200
	ds_read_b64_tr_b16 v[202:203], v202
	v_add_u32_e32 v171, v171, v139
	ds_read_b64_tr_b16 v[216:217], v216
	ds_read_b64_tr_b16 v[218:219], v218
	ds_read_b64_tr_b16 v[220:221], v171
	ds_read_b64_tr_b16 v[222:223], v222
	s_setprio 1
	s_waitcnt lgkmcnt(6)
	v_mfma_f32_16x16x32_bf16 v[196:199], v[196:199], v[172:175], v[204:207]
	s_waitcnt lgkmcnt(4)
	v_mfma_f32_16x16x32_bf16 v[200:203], v[200:203], v[172:175], v[208:211]
	s_waitcnt lgkmcnt(2)
	v_mfma_f32_16x16x32_bf16 v[204:207], v[216:219], v[172:175], v[212:215]
	s_waitcnt lgkmcnt(0)
	v_mfma_f32_16x16x32_bf16 v[172:175], v[220:223], v[172:175], v[180:183]
	s_setprio 0
	v_cvt_pk_bf16_f32 v180, v100, v101
	v_add_u32_e32 v100, s60, v155
	v_and_b32_e32 v100, 0x80, v100
	v_or3_b32 v100, v100, v152, v135
	v_add_u32_e32 v101, s60, v154
	v_and_b32_e32 v101, 0x80, v101
	v_lshl_add_u32 v100, v100, 8, s54
	v_cvt_pk_bf16_f32 v181, v162, v164
	v_or3_b32 v101, v101, v152, v136
	v_add_u32_e32 v162, v100, v99
	v_lshl_add_u32 v101, v101, 8, s54
	v_add_u32_e32 v164, v162, v138
	v_add_u32_e32 v162, v162, v139
	ds_read_b64_tr_b16 v[208:209], v164
	ds_read_b64_tr_b16 v[212:213], v162
	v_add_u32_e32 v164, v101, v99
	v_cvt_pk_bf16_f32 v182, v166, v167
	v_add_u32_e32 v166, v164, v138
	v_add_u32_e32 v162, v164, v139
	ds_read_b64_tr_b16 v[210:211], v166
	ds_read_b64_tr_b16 v[214:215], v162
	v_add_u32_e32 v162, v100, v163
	v_add_u32_e32 v164, v162, v138
	v_add_u32_e32 v162, v162, v139
	ds_read_b64_tr_b16 v[216:217], v164
	ds_read_b64_tr_b16 v[220:221], v162
	v_add_u32_e32 v164, v101, v163
	v_add_u32_e32 v166, v164, v138
	v_add_u32_e32 v162, v164, v139
	ds_read_b64_tr_b16 v[218:219], v166
	ds_read_b64_tr_b16 v[222:223], v162
	v_cvt_pk_bf16_f32 v183, v168, v170
	s_setprio 1
	s_waitcnt lgkmcnt(5)
	v_mfma_f32_16x16x32_bf16 v[176:179], v[208:211], v[180:183], v[176:179]
	s_waitcnt lgkmcnt(4)
	v_mfma_f32_16x16x32_bf16 v[184:187], v[212:215], v[180:183], v[184:187]
	s_waitcnt lgkmcnt(1)
	v_mfma_f32_16x16x32_bf16 v[188:191], v[216:219], v[180:183], v[188:191]
	s_waitcnt lgkmcnt(0)
	v_mfma_f32_16x16x32_bf16 v[192:195], v[220:223], v[180:183], v[192:195]
	s_setprio 0
	v_add_u32_e32 v162, v100, v165
	v_add_u32_e32 v164, v162, v138
	v_add_u32_e32 v166, v101, v165
	v_add_u32_e32 v162, v162, v139
	v_add_u32_e32 v100, v100, v169
	v_add_u32_e32 v167, v166, v138
	v_add_u32_e32 v166, v166, v139
	ds_read_b64_tr_b16 v[208:209], v164
	ds_read_b64_tr_b16 v[210:211], v167
	ds_read_b64_tr_b16 v[212:213], v162
	ds_read_b64_tr_b16 v[214:215], v166
	v_add_u32_e32 v162, v100, v138
	v_add_u32_e32 v101, v101, v169
	v_add_u32_e32 v164, v101, v138
	v_add_u32_e32 v100, v100, v139
	v_add_u32_e32 v101, v101, v139
	ds_read_b64_tr_b16 v[216:217], v162
	ds_read_b64_tr_b16 v[218:219], v164
	ds_read_b64_tr_b16 v[220:221], v100
	ds_read_b64_tr_b16 v[222:223], v101
	s_setprio 1
	s_waitcnt lgkmcnt(6)
	v_mfma_f32_16x16x32_bf16 v[196:199], v[208:211], v[180:183], v[196:199]
	s_waitcnt lgkmcnt(4)
	v_mfma_f32_16x16x32_bf16 v[200:203], v[212:215], v[180:183], v[200:203]
	s_waitcnt lgkmcnt(2)
	v_mfma_f32_16x16x32_bf16 v[204:207], v[216:219], v[180:183], v[204:207]
	s_waitcnt lgkmcnt(0)
	v_mfma_f32_16x16x32_bf16 v[170:173], v[220:223], v[180:183], v[172:175]
	s_setprio 0
	v_cvt_pk_bf16_f32 v2, v2, v3
	v_cvt_pk_bf16_f32 v3, v5, v98
	v_add_u32_e32 v98, s60, v153
	v_and_b32_e32 v98, 0x80, v98
	v_or3_b32 v98, v98, v152, v137
	v_lshl_add_u32 v162, v98, 8, s54
	v_add_u32_e32 v100, v162, v99
	v_add_u32_e32 v98, v100, v138
	v_add_u32_e32 v100, v100, v139
	ds_read_b64_tr_b16 v[98:99], v98
	ds_read_b64_tr_b16 v[174:175], v100
	v_add_u32_e32 v100, v162, v163
	v_add_u32_e32 v101, v100, v138
	v_add_u32_e32 v100, v100, v139
	ds_read_b64_tr_b16 v[180:181], v101
	ds_read_b64_tr_b16 v[208:209], v100
	v_mov_b32_e32 v5, v4
	s_setprio 1
	s_waitcnt lgkmcnt(3)
	v_mov_b32_e32 v100, v98
	v_mov_b32_e32 v101, v99
	s_waitcnt lgkmcnt(1)
	v_mov_b32_e32 v182, v180
	v_mov_b32_e32 v183, v181
	s_waitcnt lgkmcnt(0)
	v_mov_b32_e32 v210, v208
	v_mfma_f32_16x16x32_bf16 v[98:101], v[98:101], v[2:5], v[176:179]
	v_mov_b32_e32 v211, v209
	s_nop 1
	v_mov_b32_e32 v176, v174
	v_mov_b32_e32 v177, v175
	v_mfma_f32_16x16x32_bf16 v[178:181], v[180:183], v[2:5], v[188:191]
	s_nop 0
	v_mfma_f32_16x16x32_bf16 v[174:177], v[174:177], v[2:5], v[184:187]
	v_mfma_f32_16x16x32_bf16 v[182:185], v[208:211], v[2:5], v[192:195]
	s_setprio 0
	v_add_u32_e32 v163, v162, v165
	v_add_u32_e32 v164, v163, v138
	v_add_u32_e32 v162, v162, v169
	v_add_u32_e32 v165, v163, v139
	v_add_u32_e32 v168, v162, v138
	v_add_u32_e32 v169, v162, v139
	ds_read_b64_tr_b16 v[162:163], v164
	ds_read_b64_tr_b16 v[166:167], v165
	ds_read_b64_tr_b16 v[186:187], v168
	ds_read_b64_tr_b16 v[190:191], v169
	s_setprio 1
	s_waitcnt lgkmcnt(3)
	v_mov_b32_e32 v164, v162
	v_mov_b32_e32 v165, v163
	s_waitcnt lgkmcnt(2)
	v_mov_b32_e32 v168, v166
	v_mov_b32_e32 v169, v167
	s_waitcnt lgkmcnt(1)
	v_mov_b32_e32 v188, v186
	v_mov_b32_e32 v189, v187
	s_waitcnt lgkmcnt(0)
	v_mov_b32_e32 v192, v190
	v_mov_b32_e32 v193, v191
	v_mfma_f32_16x16x32_bf16 v[162:165], v[162:165], v[2:5], v[196:199]
	v_mfma_f32_16x16x32_bf16 v[166:169], v[166:169], v[2:5], v[200:203]
	v_mfma_f32_16x16x32_bf16 v[186:189], v[186:189], v[2:5], v[204:207]
	v_mfma_f32_16x16x32_bf16 v[170:173], v[190:193], v[2:5], v[170:173]
	s_setprio 0
	v_lshl_add_u64 v[2:3], v[94:95], 0, s[86:87]
	v_lshlrev_b64 v[2:3], 10, v[2:3]
	v_cvt_pk_bf16_f32 v101, v100, v101
	v_cvt_pk_bf16_f32 v100, v174, v175
	v_lshl_add_u64 v[2:3], v[106:107], 0, v[2:3]
	v_cvt_pk_bf16_f32 v5, v98, v99
	v_cvt_pk_bf16_f32 v174, v176, v177
	s_nop 0
	v_cndmask_b32_e64 v98, v100, v5, s[6:7]
	v_cndmask_b32_e64 v99, v174, v101, s[6:7]
	v_cndmask_b32_e64 v100, v5, v100, s[6:7]
	v_cndmask_b32_e64 v101, v101, v174, s[6:7]
	global_store_dwordx4 v[2:3], v[98:101], off sc1
	v_cvt_pk_bf16_f32 v5, v178, v179
	v_cvt_pk_bf16_f32 v174, v184, v185
	s_nop 1
	v_cvt_pk_bf16_f32 v101, v180, v181
	v_cvt_pk_bf16_f32 v100, v182, v183
	s_nop 0
	v_cndmask_b32_e64 v98, v100, v5, s[6:7]
	v_cndmask_b32_e64 v99, v174, v101, s[6:7]
	v_cndmask_b32_e64 v100, v5, v100, s[6:7]
	v_cndmask_b32_e64 v101, v101, v174, s[6:7]
	global_store_dwordx4 v[2:3], v[98:101], off offset:64 sc1
	v_cvt_pk_bf16_f32 v5, v162, v163
	v_cvt_pk_bf16_f32 v162, v168, v169
	s_nop 1
	v_cvt_pk_bf16_f32 v101, v164, v165
	v_cvt_pk_bf16_f32 v100, v166, v167
	s_nop 0
	v_cndmask_b32_e64 v98, v100, v5, s[6:7]
	v_cndmask_b32_e64 v99, v162, v101, s[6:7]
	v_cndmask_b32_e64 v100, v5, v100, s[6:7]
	v_cndmask_b32_e64 v101, v101, v162, s[6:7]
	global_store_dwordx4 v[2:3], v[98:101], off offset:128 sc1
	v_cvt_pk_bf16_f32 v5, v186, v187
	v_cvt_pk_bf16_f32 v162, v172, v173
	s_nop 1
	v_cvt_pk_bf16_f32 v101, v188, v189
	v_cvt_pk_bf16_f32 v100, v170, v171
	s_nop 0
	v_cndmask_b32_e64 v98, v100, v5, s[6:7]
	v_cndmask_b32_e64 v99, v162, v101, s[6:7]
	v_cndmask_b32_e64 v100, v5, v100, s[6:7]
	v_cndmask_b32_e64 v101, v101, v162, s[6:7]
	global_store_dwordx4 v[2:3], v[98:101], off offset:192 sc1
	s_and_saveexec_b64 s[52:53], s[8:9]
	s_cbranch_execz .LBB0_589
	v_add_f32_e32 v5, v96, v97
	v_lshl_add_u64 v[2:3], v[94:95], 2, s[48:49]
	global_store_dword v[2:3], v5, off sc1

.LBB0_598:
	s_and_saveexec_b64 s[2:3], vcc
	s_cbranch_execz .LBB0_593
	s_lshl_b32 s6, s14, 5
	s_or_b32 s6, s6, s39
	s_ashr_i32 s7, s6, 31
	s_lshl_b32 s14, s85, 2
	s_add_u32 s8, s22, s14
	s_addc_u32 s9, s23, 0
	s_add_u32 s14, s20, s14
	s_addc_u32 s15, s21, 0
	s_lshl_b64 s[6:7], s[6:7], 9
	v_lshl_add_u64 v[6:7], s[6:7], 0, v[78:79]
	v_lshlrev_b64 v[6:7], 2, v[6:7]
	v_lshl_add_u64 v[8:9], s[14:15], 0, v[6:7]
	v_add_co_u32_e32 v8, vcc, 0x500000, v8
	v_lshl_add_u64 v[6:7], s[8:9], 0, v[6:7]
	s_nop 0
	v_addc_co_u32_e32 v9, vcc, 0, v9, vcc
	v_add_co_u32_e32 v6, vcc, 0x540000, v6
	global_store_dword v[8:9], v111, off sc1
	s_nop 0
	v_addc_co_u32_e32 v7, vcc, 0, v7, vcc
	global_store_dword v[6:7], v109, off sc1
	s_branch .LBB0_593

.LBB0_702:
	v_lshl_or_b32 v196, s60, 8, v226
	v_lshl_add_u32 v194, s61, 8, v5
	v_ashrrev_i32_e32 v197, 31, v196
	v_lshlrev_b64 v[222:223], 1, v[196:197]
	v_ashrrev_i32_e32 v195, 31, v194
	v_lshl_add_u64 v[126:127], s[4:5], 0, v[222:223]
	v_lshlrev_b64 v[224:225], 11, v[194:195]
	v_lshl_add_u64 v[128:129], v[126:127], 0, v[224:225]
	global_load_dwordx4 v[230:233], v[128:129], off
	global_load_dwordx4 v[190:193], v[128:129], off offset:64
	v_or_b32_e32 v128, 16, v194
	v_ashrrev_i32_e32 v129, 31, v128
	v_lshlrev_b64 v[220:221], 11, v[128:129]
	v_lshl_add_u64 v[128:129], v[126:127], 0, v[220:221]
	global_load_dwordx4 v[186:189], v[128:129], off
	global_load_dwordx4 v[182:185], v[128:129], off offset:64
	v_or_b32_e32 v128, 32, v194
	v_ashrrev_i32_e32 v129, 31, v128
	v_lshlrev_b64 v[218:219], 11, v[128:129]
	v_lshl_add_u64 v[128:129], v[126:127], 0, v[218:219]
	global_load_dwordx4 v[178:181], v[128:129], off
	global_load_dwordx4 v[174:177], v[128:129], off offset:64
	v_or_b32_e32 v128, 48, v194
	v_ashrrev_i32_e32 v129, 31, v128
	s_mov_b64 s[22:23], 0x40000
	v_lshlrev_b64 v[216:217], 11, v[128:129]
	v_lshl_add_u64 v[214:215], v[224:225], 0, s[22:23]
	s_mov_b64 s[22:23], 0x48000
	v_lshl_add_u64 v[128:129], v[126:127], 0, v[216:217]
	v_lshl_add_u64 v[212:213], v[224:225], 0, s[22:23]
	s_mov_b64 s[22:23], 0x50000
	global_load_dwordx4 v[170:173], v[128:129], off
	global_load_dwordx4 v[166:169], v[128:129], off offset:64
	v_lshl_add_u64 v[128:129], v[126:127], 0, v[214:215]
	v_lshl_add_u64 v[200:201], v[224:225], 0, s[22:23]
	s_mov_b64 s[22:23], 0x58000
	global_load_dwordx4 v[162:165], v[128:129], off
	global_load_dwordx4 v[158:161], v[128:129], off offset:64
	v_lshl_add_u64 v[128:129], v[126:127], 0, v[212:213]
	v_lshl_add_u64 v[198:199], v[224:225], 0, s[22:23]
	global_load_dwordx4 v[154:157], v[128:129], off
	global_load_dwordx4 v[150:153], v[128:129], off offset:64
	v_lshl_add_u64 v[128:129], v[126:127], 0, v[200:201]
	v_lshl_add_u64 v[126:127], v[126:127], 0, v[198:199]
	global_load_dwordx4 v[146:149], v[128:129], off
	global_load_dwordx4 v[138:141], v[128:129], off offset:64
	global_load_dwordx4 v[142:145], v[126:127], off
	s_nop 0
	global_load_dwordx4 v[126:129], v[126:127], off offset:64
	s_lshl_b32 s13, s60, 2
	s_or_b32 s22, s13, s56
	s_ashr_i32 s23, s22, 31
	s_lshl_b64 s[22:23], s[22:23], 14
	s_waitcnt vmcnt(0)
	v_lshlrev_b32_e32 v242, 16, v230
	v_and_b32_e32 v243, 0xffff0000, v230
	v_lshlrev_b32_e32 v230, 16, v231
	v_and_b32_e32 v231, 0xffff0000, v231
	v_pk_add_f32 v[132:133], v[132:133], v[230:231]
	v_pk_add_f32 v[130:131], v[130:131], v[242:243]
	v_lshlrev_b32_e32 v244, 16, v232
	v_and_b32_e32 v245, 0xffff0000, v232
	v_mul_f32_e32 v229, v131, v131
	v_mul_f32_e32 v230, v133, v133
	v_pk_add_f32 v[134:135], v[134:135], v[244:245]
	v_fmac_f32_e32 v229, v130, v130
	v_fmac_f32_e32 v230, v132, v132
	v_add_f32_e32 v229, v229, v230
	v_mul_f32_e32 v230, v135, v135
	v_lshlrev_b32_e32 v232, 16, v233
	v_and_b32_e32 v233, 0xffff0000, v233
	v_fmac_f32_e32 v230, v134, v134
	v_cvt_pk_bf16_f32 v130, v130, v131
	v_cvt_pk_bf16_f32 v131, v132, v133
	v_cvt_pk_bf16_f32 v132, v134, v135
	v_lshl_add_u64 v[134:135], s[4:5], 0, v[224:225]
	v_pk_add_f32 v[136:137], v[136:137], v[232:233]
	v_lshl_add_u64 v[134:135], v[134:135], 0, v[222:223]
	v_cvt_pk_bf16_f32 v133, v136, v137
	v_mul_f32_e32 v231, v137, v137
	global_store_dwordx4 v[134:135], v[130:133], off sc1
	v_fmac_f32_e32 v231, v136, v136
	v_lshlrev_b32_e32 v136, 16, v192
	v_lshlrev_b32_e32 v130, 16, v190
	v_and_b32_e32 v131, 0xffff0000, v190
	v_lshlrev_b32_e32 v132, 16, v191
	v_and_b32_e32 v133, 0xffff0000, v191
	v_and_b32_e32 v137, 0xffff0000, v192
	v_lshlrev_b32_e32 v190, 16, v193
	v_and_b32_e32 v191, 0xffff0000, v193
	v_pk_add_f32 v[124:125], v[124:125], v[132:133]
	v_pk_add_f32 v[122:123], v[122:123], v[130:131]
	v_pk_add_f32 v[130:131], v[120:121], v[190:191]
	v_pk_add_f32 v[120:121], v[118:119], v[136:137]
	v_mul_f32_e32 v118, v123, v123
	v_mul_f32_e32 v119, v125, v125
	v_fmac_f32_e32 v118, v122, v122
	v_fmac_f32_e32 v119, v124, v124
	v_add_f32_e32 v118, v118, v119
	v_mul_f32_e32 v119, v121, v121
	v_mul_f32_e32 v132, v131, v131
	v_fmac_f32_e32 v119, v120, v120
	v_fmac_f32_e32 v132, v130, v130
	v_add_f32_e32 v230, v230, v231
	v_add_f32_e32 v119, v119, v132
	v_add_f32_e32 v229, v229, v230
	v_add_f32_e32 v118, v118, v119
	v_add_f32_e32 v132, v229, v118
	v_cvt_pk_bf16_f32 v118, v122, v123
	v_cvt_pk_bf16_f32 v119, v124, v125
	v_cvt_pk_bf16_f32 v120, v120, v121
	v_cvt_pk_bf16_f32 v121, v130, v131
	global_store_dwordx4 v[134:135], v[118:121], off offset:64 sc1
	s_nop 1
	v_mov_b32_e32 v118, v132
	s_nop 1
	v_permlane16_swap_b32_e32 v132, v118
	v_add_f32_e32 v118, v132, v118
	v_mov_b32_e32 v119, v118
	s_nop 1
	v_permlane32_swap_b32_e32 v118, v119
	s_and_saveexec_b64 s[24:25], s[6:7]
	s_cbranch_execz .LBB0_704
	s_add_u32 s26, s54, s22
	s_addc_u32 s27, s55, s23
	v_lshl_add_u64 v[120:121], v[194:195], 2, s[26:27]
	v_add_f32_e32 v118, v118, v119
	global_store_dword v[120:121], v118, off sc1
.LBB0_704:
	s_or_b64 exec, exec, s[24:25]
	v_lshlrev_b32_e32 v118, 16, v186
	v_and_b32_e32 v119, 0xffff0000, v186
	v_lshlrev_b32_e32 v120, 16, v187
	v_and_b32_e32 v121, 0xffff0000, v187
	v_lshlrev_b32_e32 v122, 16, v188
	v_and_b32_e32 v123, 0xffff0000, v188
	v_lshlrev_b32_e32 v124, 16, v189
	v_and_b32_e32 v125, 0xffff0000, v189
	v_pk_add_f32 v[116:117], v[116:117], v[120:121]
	v_pk_add_f32 v[114:115], v[114:115], v[118:119]
	v_pk_add_f32 v[118:119], v[112:113], v[124:125]
	v_pk_add_f32 v[112:113], v[110:111], v[122:123]
	v_mul_f32_e32 v110, v115, v115
	v_mul_f32_e32 v111, v117, v117
	v_fmac_f32_e32 v110, v114, v114
	v_fmac_f32_e32 v111, v116, v116
	v_add_f32_e32 v110, v110, v111
	v_mul_f32_e32 v111, v113, v113
	v_mul_f32_e32 v120, v119, v119
	v_fmac_f32_e32 v111, v112, v112
	v_fmac_f32_e32 v120, v118, v118
	v_add_f32_e32 v111, v111, v120
	v_add_f32_e32 v120, v110, v111
	v_cvt_pk_bf16_f32 v110, v114, v115
	v_lshl_add_u64 v[114:115], s[4:5], 0, v[220:221]
	v_cvt_pk_bf16_f32 v111, v116, v117
	v_cvt_pk_bf16_f32 v112, v112, v113
	v_cvt_pk_bf16_f32 v113, v118, v119
	v_lshl_add_u64 v[114:115], v[196:197], 1, v[114:115]
	global_store_dwordx4 v[114:115], v[110:113], off sc1
	v_lshlrev_b32_e32 v116, 16, v184
	v_and_b32_e32 v117, 0xffff0000, v184
	v_lshlrev_b32_e32 v110, 16, v182
	v_and_b32_e32 v111, 0xffff0000, v182
	v_lshlrev_b32_e32 v112, 16, v183
	v_and_b32_e32 v113, 0xffff0000, v183
	v_lshlrev_b32_e32 v118, 16, v185
	v_and_b32_e32 v119, 0xffff0000, v185
	v_pk_add_f32 v[108:109], v[108:109], v[112:113]
	v_pk_add_f32 v[106:107], v[106:107], v[110:111]
	v_pk_add_f32 v[110:111], v[104:105], v[118:119]
	v_pk_add_f32 v[104:105], v[102:103], v[116:117]
	v_mul_f32_e32 v102, v107, v107
	v_mul_f32_e32 v103, v109, v109
	v_fmac_f32_e32 v102, v106, v106
	v_fmac_f32_e32 v103, v108, v108
	v_add_f32_e32 v102, v102, v103
	v_mul_f32_e32 v103, v105, v105
	v_mul_f32_e32 v112, v111, v111
	v_fmac_f32_e32 v103, v104, v104
	v_fmac_f32_e32 v112, v110, v110
	v_add_f32_e32 v103, v103, v112
	v_add_f32_e32 v102, v102, v103
	v_add_f32_e32 v112, v120, v102
	v_cvt_pk_bf16_f32 v102, v106, v107
	v_cvt_pk_bf16_f32 v103, v108, v109
	v_cvt_pk_bf16_f32 v104, v104, v105
	v_cvt_pk_bf16_f32 v105, v110, v111
	global_store_dwordx4 v[114:115], v[102:105], off offset:64 sc1
	s_nop 1
	v_mov_b32_e32 v102, v112
	s_nop 1
	v_permlane16_swap_b32_e32 v112, v102
	v_add_f32_e32 v102, v112, v102
	v_mov_b32_e32 v103, v102
	s_nop 1
	v_permlane32_swap_b32_e32 v102, v103
	s_and_saveexec_b64 s[24:25], s[6:7]
	s_cbranch_execz .LBB0_706
	s_add_u32 s26, s54, s22
	s_addc_u32 s27, s55, s23
	v_lshl_add_u64 v[104:105], v[194:195], 2, s[26:27]
	v_add_f32_e32 v102, v102, v103
	global_store_dword v[104:105], v102, off offset:64 sc1
.LBB0_706:
	s_or_b64 exec, exec, s[24:25]
	v_lshlrev_b32_e32 v102, 16, v178
	v_and_b32_e32 v103, 0xffff0000, v178
	v_lshlrev_b32_e32 v104, 16, v179
	v_and_b32_e32 v105, 0xffff0000, v179
	v_lshlrev_b32_e32 v106, 16, v180
	v_and_b32_e32 v107, 0xffff0000, v180
	v_lshlrev_b32_e32 v108, 16, v181
	v_and_b32_e32 v109, 0xffff0000, v181
	v_pk_add_f32 v[100:101], v[100:101], v[104:105]
	v_pk_add_f32 v[98:99], v[98:99], v[102:103]
	v_pk_add_f32 v[102:103], v[96:97], v[108:109]
	v_pk_add_f32 v[96:97], v[94:95], v[106:107]
	v_mul_f32_e32 v94, v99, v99
	v_mul_f32_e32 v95, v101, v101
	v_fmac_f32_e32 v94, v98, v98
	v_fmac_f32_e32 v95, v100, v100
	v_add_f32_e32 v94, v94, v95
	v_mul_f32_e32 v95, v97, v97
	v_mul_f32_e32 v104, v103, v103
	v_fmac_f32_e32 v95, v96, v96
	v_fmac_f32_e32 v104, v102, v102
	v_add_f32_e32 v95, v95, v104
	v_add_f32_e32 v104, v94, v95
	v_cvt_pk_bf16_f32 v94, v98, v99
	v_lshl_add_u64 v[98:99], s[4:5], 0, v[218:219]
	v_cvt_pk_bf16_f32 v95, v100, v101
	v_cvt_pk_bf16_f32 v96, v96, v97
	v_cvt_pk_bf16_f32 v97, v102, v103
	v_lshl_add_u64 v[98:99], v[196:197], 1, v[98:99]
	global_store_dwordx4 v[98:99], v[94:97], off sc1
	v_lshlrev_b32_e32 v100, 16, v176
	v_and_b32_e32 v101, 0xffff0000, v176
	v_lshlrev_b32_e32 v94, 16, v174
	v_and_b32_e32 v95, 0xffff0000, v174
	v_lshlrev_b32_e32 v96, 16, v175
	v_and_b32_e32 v97, 0xffff0000, v175
	v_lshlrev_b32_e32 v102, 16, v177
	v_and_b32_e32 v103, 0xffff0000, v177
	v_pk_add_f32 v[92:93], v[92:93], v[96:97]
	v_pk_add_f32 v[90:91], v[90:91], v[94:95]
	v_pk_add_f32 v[94:95], v[88:89], v[102:103]
	v_pk_add_f32 v[88:89], v[86:87], v[100:101]
	v_mul_f32_e32 v86, v91, v91
	v_mul_f32_e32 v87, v93, v93
	v_fmac_f32_e32 v86, v90, v90
	v_fmac_f32_e32 v87, v92, v92
	v_add_f32_e32 v86, v86, v87
	v_mul_f32_e32 v87, v89, v89
	v_mul_f32_e32 v96, v95, v95
	v_fmac_f32_e32 v87, v88, v88
	v_fmac_f32_e32 v96, v94, v94
	v_add_f32_e32 v87, v87, v96
	v_add_f32_e32 v86, v86, v87
	v_add_f32_e32 v96, v104, v86
	v_cvt_pk_bf16_f32 v86, v90, v91
	v_cvt_pk_bf16_f32 v87, v92, v93
	v_cvt_pk_bf16_f32 v88, v88, v89
	v_cvt_pk_bf16_f32 v89, v94, v95
	global_store_dwordx4 v[98:99], v[86:89], off offset:64 sc1
	s_nop 1
	v_mov_b32_e32 v86, v96
	s_nop 1
	v_permlane16_swap_b32_e32 v96, v86
	v_add_f32_e32 v86, v96, v86
	v_mov_b32_e32 v87, v86
	s_nop 1
	v_permlane32_swap_b32_e32 v86, v87
	s_and_saveexec_b64 s[24:25], s[6:7]
	s_cbranch_execz .LBB0_708
	s_add_u32 s26, s54, s22
	s_addc_u32 s27, s55, s23
	v_lshl_add_u64 v[88:89], v[194:195], 2, s[26:27]
	v_add_f32_e32 v86, v86, v87
	global_store_dword v[88:89], v86, off offset:128 sc1
.LBB0_708:
	s_or_b64 exec, exec, s[24:25]
	v_lshlrev_b32_e32 v86, 16, v170
	v_and_b32_e32 v87, 0xffff0000, v170
	v_lshlrev_b32_e32 v88, 16, v171
	v_and_b32_e32 v89, 0xffff0000, v171
	v_lshlrev_b32_e32 v90, 16, v172
	v_and_b32_e32 v91, 0xffff0000, v172
	v_lshlrev_b32_e32 v92, 16, v173
	v_and_b32_e32 v93, 0xffff0000, v173
	v_pk_add_f32 v[84:85], v[84:85], v[88:89]
	v_pk_add_f32 v[82:83], v[82:83], v[86:87]
	v_pk_add_f32 v[86:87], v[80:81], v[92:93]
	v_pk_add_f32 v[80:81], v[78:79], v[90:91]
	v_mul_f32_e32 v78, v83, v83
	v_mul_f32_e32 v79, v85, v85
	v_fmac_f32_e32 v78, v82, v82
	v_fmac_f32_e32 v79, v84, v84
	v_add_f32_e32 v78, v78, v79
	v_mul_f32_e32 v79, v81, v81
	v_mul_f32_e32 v88, v87, v87
	v_fmac_f32_e32 v79, v80, v80
	v_fmac_f32_e32 v88, v86, v86
	v_add_f32_e32 v79, v79, v88
	v_add_f32_e32 v88, v78, v79
	v_cvt_pk_bf16_f32 v78, v82, v83
	v_lshl_add_u64 v[82:83], s[4:5], 0, v[216:217]
	v_cvt_pk_bf16_f32 v79, v84, v85
	v_cvt_pk_bf16_f32 v80, v80, v81
	v_cvt_pk_bf16_f32 v81, v86, v87
	v_lshl_add_u64 v[82:83], v[196:197], 1, v[82:83]
	global_store_dwordx4 v[82:83], v[78:81], off sc1
	v_lshlrev_b32_e32 v84, 16, v168
	v_and_b32_e32 v85, 0xffff0000, v168
	v_lshlrev_b32_e32 v78, 16, v166
	v_and_b32_e32 v79, 0xffff0000, v166
	v_lshlrev_b32_e32 v80, 16, v167
	v_and_b32_e32 v81, 0xffff0000, v167
	v_lshlrev_b32_e32 v86, 16, v169
	v_and_b32_e32 v87, 0xffff0000, v169
	v_pk_add_f32 v[76:77], v[76:77], v[80:81]
	v_pk_add_f32 v[74:75], v[74:75], v[78:79]
	v_pk_add_f32 v[78:79], v[72:73], v[86:87]
	v_pk_add_f32 v[72:73], v[70:71], v[84:85]
	v_mul_f32_e32 v70, v75, v75
	v_mul_f32_e32 v71, v77, v77
	v_fmac_f32_e32 v70, v74, v74
	v_fmac_f32_e32 v71, v76, v76
	v_add_f32_e32 v70, v70, v71
	v_mul_f32_e32 v71, v73, v73
	v_mul_f32_e32 v80, v79, v79
	v_fmac_f32_e32 v71, v72, v72
	v_fmac_f32_e32 v80, v78, v78
	v_add_f32_e32 v71, v71, v80
	v_add_f32_e32 v70, v70, v71
	v_add_f32_e32 v80, v88, v70
	v_cvt_pk_bf16_f32 v70, v74, v75
	v_cvt_pk_bf16_f32 v71, v76, v77
	v_cvt_pk_bf16_f32 v72, v72, v73
	v_cvt_pk_bf16_f32 v73, v78, v79
	global_store_dwordx4 v[82:83], v[70:73], off offset:64 sc1
	s_nop 1
	v_mov_b32_e32 v70, v80
	s_nop 1
	v_permlane16_swap_b32_e32 v80, v70
	v_add_f32_e32 v70, v80, v70
	v_mov_b32_e32 v71, v70
	s_nop 1
	v_permlane32_swap_b32_e32 v70, v71
	s_and_saveexec_b64 s[24:25], s[6:7]
	s_cbranch_execz .LBB0_710
	s_add_u32 s26, s54, s22
	s_addc_u32 s27, s55, s23
	v_lshl_add_u64 v[72:73], v[194:195], 2, s[26:27]
	v_add_f32_e32 v70, v70, v71
	global_store_dword v[72:73], v70, off offset:192 sc1
.LBB0_710:
	s_or_b64 exec, exec, s[24:25]
	v_lshlrev_b32_e32 v70, 16, v162
	v_and_b32_e32 v71, 0xffff0000, v162
	v_lshlrev_b32_e32 v72, 16, v163
	v_and_b32_e32 v73, 0xffff0000, v163
	v_lshlrev_b32_e32 v74, 16, v164
	v_and_b32_e32 v75, 0xffff0000, v164
	v_lshlrev_b32_e32 v76, 16, v165
	v_and_b32_e32 v77, 0xffff0000, v165
	v_pk_add_f32 v[68:69], v[68:69], v[72:73]
	v_pk_add_f32 v[66:67], v[66:67], v[70:71]
	v_pk_add_f32 v[70:71], v[64:65], v[76:77]
	v_pk_add_f32 v[64:65], v[62:63], v[74:75]
	v_mul_f32_e32 v62, v67, v67
	v_mul_f32_e32 v63, v69, v69
	v_fmac_f32_e32 v62, v66, v66
	v_fmac_f32_e32 v63, v68, v68
	v_add_f32_e32 v62, v62, v63
	v_mul_f32_e32 v63, v65, v65
	v_mul_f32_e32 v72, v71, v71
	v_fmac_f32_e32 v63, v64, v64
	v_fmac_f32_e32 v72, v70, v70
	v_add_f32_e32 v63, v63, v72
	v_add_f32_e32 v72, v62, v63
	v_cvt_pk_bf16_f32 v62, v66, v67
	v_lshl_add_u64 v[66:67], s[4:5], 0, v[214:215]
	v_cvt_pk_bf16_f32 v63, v68, v69
	v_cvt_pk_bf16_f32 v64, v64, v65
	v_cvt_pk_bf16_f32 v65, v70, v71
	v_lshl_add_u64 v[66:67], v[196:197], 1, v[66:67]
	global_store_dwordx4 v[66:67], v[62:65], off sc1
	v_lshlrev_b32_e32 v68, 16, v160
	v_and_b32_e32 v69, 0xffff0000, v160
	v_lshlrev_b32_e32 v62, 16, v158
	v_and_b32_e32 v63, 0xffff0000, v158
	v_lshlrev_b32_e32 v64, 16, v159
	v_and_b32_e32 v65, 0xffff0000, v159
	v_lshlrev_b32_e32 v70, 16, v161
	v_and_b32_e32 v71, 0xffff0000, v161
	v_pk_add_f32 v[60:61], v[60:61], v[64:65]
	v_pk_add_f32 v[58:59], v[58:59], v[62:63]
	v_pk_add_f32 v[62:63], v[56:57], v[70:71]
	v_pk_add_f32 v[56:57], v[54:55], v[68:69]
	v_mul_f32_e32 v54, v59, v59
	v_mul_f32_e32 v55, v61, v61
	v_fmac_f32_e32 v54, v58, v58
	v_fmac_f32_e32 v55, v60, v60
	v_add_f32_e32 v54, v54, v55
	v_mul_f32_e32 v55, v57, v57
	v_mul_f32_e32 v64, v63, v63
	v_fmac_f32_e32 v55, v56, v56
	v_fmac_f32_e32 v64, v62, v62
	v_add_f32_e32 v55, v55, v64
	v_add_f32_e32 v54, v54, v55
	v_add_f32_e32 v64, v72, v54
	v_cvt_pk_bf16_f32 v54, v58, v59
	v_cvt_pk_bf16_f32 v55, v60, v61
	v_cvt_pk_bf16_f32 v56, v56, v57
	v_cvt_pk_bf16_f32 v57, v62, v63
	global_store_dwordx4 v[66:67], v[54:57], off offset:64 sc1
	s_nop 1
	v_mov_b32_e32 v54, v64
	s_nop 1
	v_permlane16_swap_b32_e32 v64, v54
	v_add_f32_e32 v54, v64, v54
	v_mov_b32_e32 v55, v54
	s_nop 1
	v_permlane32_swap_b32_e32 v54, v55
	s_and_saveexec_b64 s[24:25], s[6:7]
	s_cbranch_execz .LBB0_712
	s_add_u32 s26, s54, s22
	s_addc_u32 s27, s55, s23
	v_lshl_add_u64 v[56:57], v[194:195], 2, s[26:27]
	v_add_f32_e32 v54, v54, v55
	global_store_dword v[56:57], v54, off offset:512 sc1
.LBB0_712:
	s_or_b64 exec, exec, s[24:25]
	v_lshlrev_b32_e32 v54, 16, v154
	v_and_b32_e32 v55, 0xffff0000, v154
	v_lshlrev_b32_e32 v56, 16, v155
	v_and_b32_e32 v57, 0xffff0000, v155
	v_lshlrev_b32_e32 v58, 16, v156
	v_and_b32_e32 v59, 0xffff0000, v156
	v_lshlrev_b32_e32 v60, 16, v157
	v_and_b32_e32 v61, 0xffff0000, v157
	v_pk_add_f32 v[52:53], v[52:53], v[56:57]
	v_pk_add_f32 v[50:51], v[50:51], v[54:55]
	v_pk_add_f32 v[54:55], v[48:49], v[60:61]
	v_pk_add_f32 v[48:49], v[46:47], v[58:59]
	v_mul_f32_e32 v46, v51, v51
	v_mul_f32_e32 v47, v53, v53
	v_fmac_f32_e32 v46, v50, v50
	v_fmac_f32_e32 v47, v52, v52
	v_add_f32_e32 v46, v46, v47
	v_mul_f32_e32 v47, v49, v49
	v_mul_f32_e32 v56, v55, v55
	v_fmac_f32_e32 v47, v48, v48
	v_fmac_f32_e32 v56, v54, v54
	v_add_f32_e32 v47, v47, v56
	v_add_f32_e32 v56, v46, v47
	v_cvt_pk_bf16_f32 v46, v50, v51
	v_lshl_add_u64 v[50:51], s[4:5], 0, v[212:213]
	v_cvt_pk_bf16_f32 v47, v52, v53
	v_cvt_pk_bf16_f32 v48, v48, v49
	v_cvt_pk_bf16_f32 v49, v54, v55
	v_lshl_add_u64 v[50:51], v[196:197], 1, v[50:51]
	global_store_dwordx4 v[50:51], v[46:49], off sc1
	v_lshlrev_b32_e32 v52, 16, v152
	v_and_b32_e32 v53, 0xffff0000, v152
	v_lshlrev_b32_e32 v46, 16, v150
	v_and_b32_e32 v47, 0xffff0000, v150
	v_lshlrev_b32_e32 v48, 16, v151
	v_and_b32_e32 v49, 0xffff0000, v151
	v_lshlrev_b32_e32 v54, 16, v153
	v_and_b32_e32 v55, 0xffff0000, v153
	v_pk_add_f32 v[44:45], v[44:45], v[48:49]
	v_pk_add_f32 v[42:43], v[42:43], v[46:47]
	v_pk_add_f32 v[46:47], v[40:41], v[54:55]
	v_pk_add_f32 v[40:41], v[38:39], v[52:53]
	v_mul_f32_e32 v38, v43, v43
	v_mul_f32_e32 v39, v45, v45
	v_fmac_f32_e32 v38, v42, v42
	v_fmac_f32_e32 v39, v44, v44
	v_add_f32_e32 v38, v38, v39
	v_mul_f32_e32 v39, v41, v41
	v_mul_f32_e32 v48, v47, v47
	v_fmac_f32_e32 v39, v40, v40
	v_fmac_f32_e32 v48, v46, v46
	v_add_f32_e32 v39, v39, v48
	v_add_f32_e32 v38, v38, v39
	v_add_f32_e32 v48, v56, v38
	v_cvt_pk_bf16_f32 v38, v42, v43
	v_cvt_pk_bf16_f32 v39, v44, v45
	v_cvt_pk_bf16_f32 v40, v40, v41
	v_cvt_pk_bf16_f32 v41, v46, v47
	global_store_dwordx4 v[50:51], v[38:41], off offset:64 sc1
	s_nop 1
	v_mov_b32_e32 v38, v48
	s_nop 1
	v_permlane16_swap_b32_e32 v48, v38
	v_add_f32_e32 v38, v48, v38
	v_mov_b32_e32 v39, v38
	s_nop 1
	v_permlane32_swap_b32_e32 v38, v39
	s_and_saveexec_b64 s[24:25], s[6:7]
	s_cbranch_execz .LBB0_714
	s_add_u32 s26, s54, s22
	s_addc_u32 s27, s55, s23
	v_lshl_add_u64 v[40:41], v[194:195], 2, s[26:27]
	v_add_f32_e32 v38, v38, v39
	global_store_dword v[40:41], v38, off offset:576 sc1
.LBB0_714:
	s_or_b64 exec, exec, s[24:25]
	v_lshlrev_b32_e32 v38, 16, v146
	v_and_b32_e32 v39, 0xffff0000, v146
	v_lshlrev_b32_e32 v40, 16, v147
	v_and_b32_e32 v41, 0xffff0000, v147
	v_lshlrev_b32_e32 v42, 16, v148
	v_and_b32_e32 v43, 0xffff0000, v148
	v_lshlrev_b32_e32 v44, 16, v149
	v_and_b32_e32 v45, 0xffff0000, v149
	v_pk_add_f32 v[36:37], v[36:37], v[40:41]
	v_pk_add_f32 v[34:35], v[34:35], v[38:39]
	v_pk_add_f32 v[38:39], v[32:33], v[44:45]
	v_pk_add_f32 v[32:33], v[30:31], v[42:43]
	v_mul_f32_e32 v30, v35, v35
	v_mul_f32_e32 v31, v37, v37
	v_fmac_f32_e32 v30, v34, v34
	v_fmac_f32_e32 v31, v36, v36
	v_add_f32_e32 v30, v30, v31
	v_mul_f32_e32 v31, v33, v33
	v_mul_f32_e32 v40, v39, v39
	v_fmac_f32_e32 v31, v32, v32
	v_fmac_f32_e32 v40, v38, v38
	v_add_f32_e32 v31, v31, v40
	v_add_f32_e32 v40, v30, v31
	v_cvt_pk_bf16_f32 v30, v34, v35
	v_lshl_add_u64 v[34:35], s[4:5], 0, v[200:201]
	v_cvt_pk_bf16_f32 v31, v36, v37
	v_cvt_pk_bf16_f32 v32, v32, v33
	v_cvt_pk_bf16_f32 v33, v38, v39
	v_lshl_add_u64 v[34:35], v[196:197], 1, v[34:35]
	global_store_dwordx4 v[34:35], v[30:33], off sc1
	v_lshlrev_b32_e32 v36, 16, v140
	v_and_b32_e32 v37, 0xffff0000, v140
	v_lshlrev_b32_e32 v30, 16, v138
	v_and_b32_e32 v31, 0xffff0000, v138
	v_lshlrev_b32_e32 v32, 16, v139
	v_and_b32_e32 v33, 0xffff0000, v139
	v_lshlrev_b32_e32 v38, 16, v141
	v_and_b32_e32 v39, 0xffff0000, v141
	v_pk_add_f32 v[28:29], v[28:29], v[32:33]
	v_pk_add_f32 v[26:27], v[26:27], v[30:31]
	v_pk_add_f32 v[30:31], v[24:25], v[38:39]
	v_pk_add_f32 v[24:25], v[22:23], v[36:37]
	v_mul_f32_e32 v22, v27, v27
	v_mul_f32_e32 v23, v29, v29
	v_fmac_f32_e32 v22, v26, v26
	v_fmac_f32_e32 v23, v28, v28
	v_add_f32_e32 v22, v22, v23
	v_mul_f32_e32 v23, v25, v25
	v_mul_f32_e32 v32, v31, v31
	v_fmac_f32_e32 v23, v24, v24
	v_fmac_f32_e32 v32, v30, v30
	v_add_f32_e32 v23, v23, v32
	v_add_f32_e32 v22, v22, v23
	v_add_f32_e32 v32, v40, v22
	v_cvt_pk_bf16_f32 v22, v26, v27
	v_cvt_pk_bf16_f32 v23, v28, v29
	v_cvt_pk_bf16_f32 v24, v24, v25
	v_cvt_pk_bf16_f32 v25, v30, v31
	global_store_dwordx4 v[34:35], v[22:25], off offset:64 sc1
	s_nop 1
	v_mov_b32_e32 v22, v32
	s_nop 1
	v_permlane16_swap_b32_e32 v32, v22
	v_add_f32_e32 v22, v32, v22
	v_mov_b32_e32 v23, v22
	s_nop 1
	v_permlane32_swap_b32_e32 v22, v23
	s_and_saveexec_b64 s[24:25], s[6:7]
	s_cbranch_execz .LBB0_716
	s_add_u32 s26, s54, s22
	s_addc_u32 s27, s55, s23
	v_lshl_add_u64 v[24:25], v[194:195], 2, s[26:27]
	v_add_f32_e32 v22, v22, v23
	global_store_dword v[24:25], v22, off offset:640 sc1
.LBB0_716:
	s_or_b64 exec, exec, s[24:25]
	v_lshlrev_b32_e32 v22, 16, v142
	v_and_b32_e32 v23, 0xffff0000, v142
	v_lshlrev_b32_e32 v24, 16, v143
	v_and_b32_e32 v25, 0xffff0000, v143
	v_lshlrev_b32_e32 v26, 16, v144
	v_and_b32_e32 v27, 0xffff0000, v144
	v_lshlrev_b32_e32 v28, 16, v145
	v_and_b32_e32 v29, 0xffff0000, v145
	v_pk_add_f32 v[20:21], v[20:21], v[24:25]
	v_pk_add_f32 v[18:19], v[18:19], v[22:23]
	v_pk_add_f32 v[22:23], v[16:17], v[28:29]
	v_pk_add_f32 v[16:17], v[14:15], v[26:27]
	v_mul_f32_e32 v14, v19, v19
	v_mul_f32_e32 v15, v21, v21
	v_fmac_f32_e32 v14, v18, v18
	v_fmac_f32_e32 v15, v20, v20
	v_add_f32_e32 v14, v14, v15
	v_mul_f32_e32 v15, v17, v17
	v_mul_f32_e32 v24, v23, v23
	v_fmac_f32_e32 v15, v16, v16
	v_fmac_f32_e32 v24, v22, v22
	v_add_f32_e32 v15, v15, v24
	v_add_f32_e32 v24, v14, v15
	v_cvt_pk_bf16_f32 v14, v18, v19
	v_lshl_add_u64 v[18:19], s[4:5], 0, v[198:199]
	v_cvt_pk_bf16_f32 v15, v20, v21
	v_cvt_pk_bf16_f32 v16, v16, v17
	v_cvt_pk_bf16_f32 v17, v22, v23
	v_lshl_add_u64 v[18:19], v[196:197], 1, v[18:19]
	global_store_dwordx4 v[18:19], v[14:17], off sc1
	v_lshlrev_b32_e32 v20, 16, v128
	v_and_b32_e32 v21, 0xffff0000, v128
	v_lshlrev_b32_e32 v14, 16, v126
	v_and_b32_e32 v15, 0xffff0000, v126
	v_lshlrev_b32_e32 v16, 16, v127
	v_and_b32_e32 v17, 0xffff0000, v127
	v_lshlrev_b32_e32 v22, 16, v129
	v_and_b32_e32 v23, 0xffff0000, v129
	v_pk_add_f32 v[12:13], v[12:13], v[16:17]
	v_pk_add_f32 v[10:11], v[10:11], v[14:15]
	v_pk_add_f32 v[14:15], v[8:9], v[22:23]
	v_pk_add_f32 v[8:9], v[6:7], v[20:21]
	v_mul_f32_e32 v6, v11, v11
	v_mul_f32_e32 v7, v13, v13
	v_fmac_f32_e32 v6, v10, v10
	v_fmac_f32_e32 v7, v12, v12
	v_add_f32_e32 v6, v6, v7
	v_mul_f32_e32 v7, v9, v9
	v_mul_f32_e32 v16, v15, v15
	v_fmac_f32_e32 v7, v8, v8
	v_fmac_f32_e32 v16, v14, v14
	v_add_f32_e32 v7, v7, v16
	v_add_f32_e32 v6, v6, v7
	v_add_f32_e32 v16, v24, v6
	v_cvt_pk_bf16_f32 v6, v10, v11
	v_cvt_pk_bf16_f32 v7, v12, v13
	v_cvt_pk_bf16_f32 v8, v8, v9
	v_cvt_pk_bf16_f32 v9, v14, v15
	global_store_dwordx4 v[18:19], v[6:9], off offset:64 sc1
	s_nop 1
	v_mov_b32_e32 v6, v16
	s_nop 1
	v_permlane16_swap_b32_e32 v16, v6
	v_add_f32_e32 v6, v16, v6
	v_mov_b32_e32 v7, v6
	s_nop 1
	v_permlane32_swap_b32_e32 v6, v7
	s_and_saveexec_b64 s[24:25], s[6:7]
	s_cbranch_execz .LBB0_718
	s_add_u32 s22, s54, s22
	s_addc_u32 s23, s55, s23
	v_lshl_add_u64 v[8:9], v[194:195], 2, s[22:23]
	v_add_f32_e32 v6, v6, v7
	global_store_dword v[8:9], v6, off offset:704 sc1

.LBB0_788:
	v_lshl_add_u32 v134, s64, 8, v5
	v_ashrrev_i32_e32 v135, 31, v134
	v_lshl_add_u64 v[136:137], v[134:135], 2, s[4:5]
	v_mov_b32_e32 v211, v4
	v_lshl_add_u64 v[140:141], v[136:137], 0, v[210:211]
	v_mov_b32_e32 v213, v4
	v_mov_b32_e32 v209, v4
	global_load_dword v145, v[140:141], off
	v_lshl_add_u64 v[140:141], v[136:137], 0, v[212:213]
	v_mov_b32_e32 v215, v4
	v_lshl_add_u64 v[138:139], v[136:137], 0, v[208:209]
	global_load_dword v146, v[140:141], off
	v_lshl_add_u64 v[140:141], v[136:137], 0, v[214:215]
	global_load_dword v144, v[138:139], off
	global_load_dword v148, v[138:139], off offset:64
	global_load_dword v155, v[138:139], off offset:128
	global_load_dword v159, v[138:139], off offset:192
	global_load_dword v163, v[138:139], off offset:512
	global_load_dword v167, v[138:139], off offset:576
	global_load_dword v171, v[138:139], off offset:640
	global_load_dword v147, v[140:141], off
	v_lshl_add_u64 v[140:141], v[136:137], 0, 64
	v_lshl_add_u64 v[142:143], v[140:141], 0, v[210:211]
	global_load_dword v149, v[142:143], off
	v_lshl_add_u64 v[142:143], v[140:141], 0, v[212:213]
	v_lshl_add_u64 v[140:141], v[140:141], 0, v[214:215]
	global_load_dword v150, v[142:143], off
	global_load_dword v151, v[140:141], off
	v_lshl_add_u64 v[140:141], v[136:137], 0, s[68:69]
	v_lshl_add_u64 v[142:143], v[140:141], 0, v[210:211]
	global_load_dword v156, v[142:143], off
	v_lshl_add_u64 v[142:143], v[140:141], 0, v[212:213]
	v_lshl_add_u64 v[140:141], v[140:141], 0, v[214:215]
	global_load_dword v157, v[142:143], off
	global_load_dword v158, v[140:141], off
	s_mov_b64 s[24:25], 0xc0
	v_lshl_add_u64 v[140:141], v[136:137], 0, s[24:25]
	v_lshl_add_u64 v[142:143], v[140:141], 0, v[210:211]
	global_load_dword v160, v[142:143], off
	v_lshl_add_u64 v[142:143], v[140:141], 0, v[212:213]
	v_lshl_add_u64 v[140:141], v[140:141], 0, v[214:215]
	global_load_dword v161, v[142:143], off
	global_load_dword v162, v[140:141], off
	s_mov_b64 s[24:25], 0x200
	v_lshl_add_u64 v[140:141], v[136:137], 0, s[24:25]
	v_lshl_add_u64 v[142:143], v[140:141], 0, v[210:211]
	global_load_dword v164, v[142:143], off
	v_lshl_add_u64 v[142:143], v[140:141], 0, v[212:213]
	v_lshl_add_u64 v[140:141], v[140:141], 0, v[214:215]
	global_load_dword v165, v[142:143], off
	global_load_dword v166, v[140:141], off
	s_mov_b64 s[24:25], 0x240
	v_lshl_add_u64 v[140:141], v[136:137], 0, s[24:25]
	v_lshl_add_u64 v[142:143], v[140:141], 0, v[210:211]
	global_load_dword v168, v[142:143], off
	v_lshl_add_u64 v[142:143], v[140:141], 0, v[212:213]
	v_lshl_add_u64 v[140:141], v[140:141], 0, v[214:215]
	global_load_dword v169, v[142:143], off
	global_load_dword v170, v[140:141], off
	s_mov_b64 s[24:25], 0x280
	v_lshl_add_u64 v[140:141], v[136:137], 0, s[24:25]
	v_lshl_add_u64 v[142:143], v[140:141], 0, v[210:211]
	global_load_dword v172, v[142:143], off
	v_lshl_add_u64 v[142:143], v[140:141], 0, v[212:213]
	v_lshl_add_u64 v[140:141], v[140:141], 0, v[214:215]
	global_load_dword v142, v[142:143], off
	s_mov_b64 s[24:25], 0x2c0
	global_load_dword v140, v[140:141], off
	v_lshl_add_u64 v[136:137], v[136:137], 0, s[24:25]
	global_load_dword v141, v[138:139], off offset:704
	v_lshl_add_u64 v[138:139], v[136:137], 0, v[210:211]
	global_load_dword v173, v[138:139], off
	v_lshl_add_u64 v[138:139], v[136:137], 0, v[212:213]
	v_lshl_add_u64 v[136:137], v[136:137], 0, v[214:215]
	global_load_dword v138, v[138:139], off
	s_lshl_b32 s15, s63, 2
	global_load_dword v136, v[136:137], off
	s_or_b32 s24, s15, s59
	s_ashr_i32 s25, s24, 31
	s_lshl_b64 s[24:25], s[24:25], 14
	s_waitcnt vmcnt(0)
	v_add_f32_e32 v137, v144, v145
	v_add_f32_e32 v139, v146, v147
	v_add_f32_e32 v137, v137, v139
	v_mov_b32_e32 v139, v137
	s_nop 1
	v_permlane16_swap_b32_e32 v137, v139
	v_add_f32_e32 v137, v137, v139
	v_mov_b32_e32 v139, v137
	s_nop 1
	v_permlane32_swap_b32_e32 v137, v139
	v_add_f32_e32 v137, v137, v139
	v_fmamk_f32 v137, v137, 0x3a800000, v236
	v_rsq_f32_e32 v154, v137
	v_add_f32_e32 v137, v148, v149
	v_add_f32_e32 v139, v150, v151
	v_add_f32_e32 v137, v137, v139
	v_mov_b32_e32 v139, v137
	s_nop 1
	v_permlane16_swap_b32_e32 v137, v139
	v_add_f32_e32 v152, v137, v139
	v_add_f32_e32 v137, v155, v156
	v_add_f32_e32 v139, v157, v158
	v_add_f32_e32 v137, v137, v139
	v_mov_b32_e32 v139, v137
	s_nop 1
	v_permlane16_swap_b32_e32 v137, v139
	v_add_f32_e32 v150, v137, v139
	v_add_f32_e32 v137, v159, v160
	v_add_f32_e32 v139, v161, v162
	v_add_f32_e32 v137, v137, v139
	v_mov_b32_e32 v139, v137
	s_nop 1
	v_permlane16_swap_b32_e32 v137, v139
	v_add_f32_e32 v148, v137, v139
	v_add_f32_e32 v137, v163, v164
	v_add_f32_e32 v139, v165, v166
	v_add_f32_e32 v137, v137, v139
	v_mov_b32_e32 v139, v137
	s_nop 1
	v_permlane16_swap_b32_e32 v137, v139
	v_add_f32_e32 v146, v137, v139
	v_add_f32_e32 v137, v167, v168
	v_add_f32_e32 v139, v169, v170
	v_add_f32_e32 v137, v137, v139
	v_mov_b32_e32 v139, v137
	s_nop 1
	v_permlane16_swap_b32_e32 v137, v139
	v_add_f32_e32 v144, v137, v139
	v_add_f32_e32 v137, v171, v172
	v_add_f32_e32 v139, v142, v140
	v_add_f32_e32 v137, v137, v139
	v_mov_b32_e32 v139, v137
	v_pk_mul_f32 v[132:133], v[132:133], v[154:155] op_sel_hi:[1,0]
	v_pk_mul_f32 v[130:131], v[130:131], v[154:155] op_sel_hi:[1,0]
	v_permlane16_swap_b32_e32 v137, v139
	v_pk_mul_f32 v[156:157], v[128:129], v[154:155] op_sel_hi:[1,0]
	v_pk_mul_f32 v[128:129], v[126:127], v[154:155] op_sel_hi:[1,0]
	v_mul_f32_e32 v126, v131, v131
	v_mul_f32_e32 v127, v133, v133
	v_add_f32_e32 v142, v137, v139
	v_add_f32_e32 v137, v141, v173
	v_add_f32_e32 v136, v138, v136
	v_fmac_f32_e32 v126, v130, v130
	v_fmac_f32_e32 v127, v132, v132
	v_add_f32_e32 v136, v137, v136
	v_add_f32_e32 v126, v126, v127
	v_mul_f32_e32 v127, v129, v129
	v_mov_b32_e32 v137, v136
	v_fmac_f32_e32 v127, v128, v128
	s_nop 0
	v_permlane16_swap_b32_e32 v136, v137
	v_add_f32_e32 v126, v127, v126
	v_mul_f32_e32 v127, v157, v157
	v_add_f32_e32 v140, v136, v137
	v_lshl_or_b32 v138, s63, 8, v224
	v_lshlrev_b64 v[136:137], 11, v[134:135]
	v_fmac_f32_e32 v127, v156, v156
	v_ashrrev_i32_e32 v139, 31, v138
	v_lshl_add_u64 v[136:137], s[8:9], 0, v[136:137]
	v_add_f32_e32 v155, v127, v126
	v_lshl_add_u64 v[136:137], v[138:139], 1, v[136:137]
	v_cvt_pk_bf16_f32 v126, v130, v131
	v_cvt_pk_bf16_f32 v127, v132, v133
	v_pk_mul_f32 v[124:125], v[124:125], v[154:155] op_sel_hi:[1,0]
	v_pk_mul_f32 v[122:123], v[122:123], v[154:155] op_sel_hi:[1,0]
	v_cvt_pk_bf16_f32 v128, v128, v129
	v_cvt_pk_bf16_f32 v129, v156, v157
	global_store_dwordx4 v[136:137], v[126:129], off sc1
	v_mov_b32_e32 v153, v152
	v_mov_b32_e32 v151, v150
	v_pk_mul_f32 v[126:127], v[120:121], v[154:155] op_sel_hi:[1,0]
	v_pk_mul_f32 v[120:121], v[118:119], v[154:155] op_sel_hi:[1,0]
	v_mul_f32_e32 v118, v123, v123
	v_mul_f32_e32 v119, v125, v125
	v_fmac_f32_e32 v118, v122, v122
	v_fmac_f32_e32 v119, v124, v124
	v_add_f32_e32 v118, v118, v119
	v_mul_f32_e32 v119, v121, v121
	v_fmac_f32_e32 v119, v120, v120
	v_add_f32_e32 v118, v119, v118
	v_mul_f32_e32 v119, v127, v127
	v_fmac_f32_e32 v119, v126, v126
	v_add_f32_e32 v118, v119, v118
	v_add_f32_e32 v128, v155, v118
	v_cvt_pk_bf16_f32 v118, v122, v123
	v_cvt_pk_bf16_f32 v119, v124, v125
	v_cvt_pk_bf16_f32 v120, v120, v121
	v_cvt_pk_bf16_f32 v121, v126, v127
	global_store_dwordx4 v[136:137], v[118:121], off offset:64 sc1
	v_mov_b32_e32 v149, v148
	v_mov_b32_e32 v147, v146
	v_mov_b32_e32 v118, v128
	s_nop 1
	v_permlane16_swap_b32_e32 v128, v118
	v_add_f32_e32 v118, v128, v118
	v_mov_b32_e32 v145, v144
	v_mov_b32_e32 v143, v142
	v_mov_b32_e32 v141, v140
	v_mov_b32_e32 v119, v118
	v_permlane32_swap_b32_e32 v152, v153
	v_permlane32_swap_b32_e32 v150, v151
	v_permlane32_swap_b32_e32 v148, v149
	v_permlane32_swap_b32_e32 v146, v147
	v_permlane32_swap_b32_e32 v144, v145
	v_permlane32_swap_b32_e32 v142, v143
	v_permlane32_swap_b32_e32 v140, v141
	v_permlane32_swap_b32_e32 v118, v119
	s_and_saveexec_b64 s[26:27], s[6:7]
	s_cbranch_execz .LBB0_790
	s_add_u32 s28, s57, s24
	s_addc_u32 s29, s58, s25
	v_lshl_add_u64 v[120:121], v[134:135], 2, s[28:29]
	v_add_f32_e32 v118, v118, v119
	global_store_dword v[120:121], v118, off sc1
.LBB0_790:
	s_or_b64 exec, exec, s[26:27]
	v_add_f32_e32 v118, v152, v153
	v_fmamk_f32 v118, v118, 0x3a800000, v236
	v_rsq_f32_e32 v118, v118
	v_or_b32_e32 v120, 16, v134
	v_ashrrev_i32_e32 v121, 31, v120
	v_lshlrev_b64 v[120:121], 11, v[120:121]
	v_pk_mul_f32 v[116:117], v[116:117], v[118:119] op_sel_hi:[1,0]
	v_pk_mul_f32 v[114:115], v[114:115], v[118:119] op_sel_hi:[1,0]
	v_pk_mul_f32 v[122:123], v[112:113], v[118:119] op_sel_hi:[1,0]
	v_pk_mul_f32 v[112:113], v[110:111], v[118:119] op_sel_hi:[1,0]
	v_mul_f32_e32 v110, v115, v115
	v_mul_f32_e32 v111, v117, v117
	v_fmac_f32_e32 v110, v114, v114
	v_fmac_f32_e32 v111, v116, v116
	v_add_f32_e32 v110, v110, v111
	v_mul_f32_e32 v111, v113, v113
	v_fmac_f32_e32 v111, v112, v112
	v_add_f32_e32 v110, v111, v110
	v_mul_f32_e32 v111, v123, v123
	v_fmac_f32_e32 v111, v122, v122
	v_lshl_add_u64 v[120:121], s[8:9], 0, v[120:121]
	v_add_f32_e32 v119, v111, v110
	v_lshl_add_u64 v[120:121], v[138:139], 1, v[120:121]
	v_cvt_pk_bf16_f32 v110, v114, v115
	v_cvt_pk_bf16_f32 v111, v116, v117
	v_pk_mul_f32 v[108:109], v[108:109], v[118:119] op_sel_hi:[1,0]
	v_pk_mul_f32 v[106:107], v[106:107], v[118:119] op_sel_hi:[1,0]
	v_cvt_pk_bf16_f32 v112, v112, v113
	v_cvt_pk_bf16_f32 v113, v122, v123
	global_store_dwordx4 v[120:121], v[110:113], off sc1
	s_nop 1
	v_pk_mul_f32 v[110:111], v[104:105], v[118:119] op_sel_hi:[1,0]
	v_pk_mul_f32 v[104:105], v[102:103], v[118:119] op_sel_hi:[1,0]
	v_mul_f32_e32 v102, v107, v107
	v_mul_f32_e32 v103, v109, v109
	v_fmac_f32_e32 v102, v106, v106
	v_fmac_f32_e32 v103, v108, v108
	v_add_f32_e32 v102, v102, v103
	v_mul_f32_e32 v103, v105, v105
	v_fmac_f32_e32 v103, v104, v104
	v_add_f32_e32 v102, v103, v102
	v_mul_f32_e32 v103, v111, v111
	v_fmac_f32_e32 v103, v110, v110
	v_add_f32_e32 v102, v103, v102
	v_add_f32_e32 v112, v119, v102
	v_cvt_pk_bf16_f32 v102, v106, v107
	v_cvt_pk_bf16_f32 v103, v108, v109
	v_cvt_pk_bf16_f32 v104, v104, v105
	v_cvt_pk_bf16_f32 v105, v110, v111
	global_store_dwordx4 v[120:121], v[102:105], off offset:64 sc1
	s_nop 1
	v_mov_b32_e32 v102, v112
	s_nop 1
	v_permlane16_swap_b32_e32 v112, v102
	v_add_f32_e32 v102, v112, v102
	v_mov_b32_e32 v103, v102
	s_nop 1
	v_permlane32_swap_b32_e32 v102, v103
	s_and_saveexec_b64 s[26:27], s[6:7]
	s_cbranch_execz .LBB0_792
	s_add_u32 s28, s57, s24
	s_addc_u32 s29, s58, s25
	v_lshl_add_u64 v[104:105], v[134:135], 2, s[28:29]
	v_add_f32_e32 v102, v102, v103
	global_store_dword v[104:105], v102, off offset:64 sc1
.LBB0_792:
	s_or_b64 exec, exec, s[26:27]
	v_add_f32_e32 v102, v150, v151
	v_fmamk_f32 v102, v102, 0x3a800000, v236
	v_rsq_f32_e32 v102, v102
	v_or_b32_e32 v104, 32, v134
	v_ashrrev_i32_e32 v105, 31, v104
	v_lshlrev_b64 v[104:105], 11, v[104:105]
	v_pk_mul_f32 v[100:101], v[100:101], v[102:103] op_sel_hi:[1,0]
	v_pk_mul_f32 v[98:99], v[98:99], v[102:103] op_sel_hi:[1,0]
	v_pk_mul_f32 v[106:107], v[96:97], v[102:103] op_sel_hi:[1,0]
	v_pk_mul_f32 v[96:97], v[94:95], v[102:103] op_sel_hi:[1,0]
	v_mul_f32_e32 v94, v99, v99
	v_mul_f32_e32 v95, v101, v101
	v_fmac_f32_e32 v94, v98, v98
	v_fmac_f32_e32 v95, v100, v100
	v_add_f32_e32 v94, v94, v95
	v_mul_f32_e32 v95, v97, v97
	v_fmac_f32_e32 v95, v96, v96
	v_add_f32_e32 v94, v95, v94
	v_mul_f32_e32 v95, v107, v107
	v_fmac_f32_e32 v95, v106, v106
	v_lshl_add_u64 v[104:105], s[8:9], 0, v[104:105]
	v_add_f32_e32 v103, v95, v94
	v_lshl_add_u64 v[104:105], v[138:139], 1, v[104:105]
	v_cvt_pk_bf16_f32 v94, v98, v99
	v_cvt_pk_bf16_f32 v95, v100, v101
	v_pk_mul_f32 v[92:93], v[92:93], v[102:103] op_sel_hi:[1,0]
	v_pk_mul_f32 v[90:91], v[90:91], v[102:103] op_sel_hi:[1,0]
	v_cvt_pk_bf16_f32 v96, v96, v97
	v_cvt_pk_bf16_f32 v97, v106, v107
	global_store_dwordx4 v[104:105], v[94:97], off sc1
	s_nop 1
	v_pk_mul_f32 v[94:95], v[88:89], v[102:103] op_sel_hi:[1,0]
	v_pk_mul_f32 v[88:89], v[86:87], v[102:103] op_sel_hi:[1,0]
	v_mul_f32_e32 v86, v91, v91
	v_mul_f32_e32 v87, v93, v93
	v_fmac_f32_e32 v86, v90, v90
	v_fmac_f32_e32 v87, v92, v92
	v_add_f32_e32 v86, v86, v87
	v_mul_f32_e32 v87, v89, v89
	v_fmac_f32_e32 v87, v88, v88
	v_add_f32_e32 v86, v87, v86
	v_mul_f32_e32 v87, v95, v95
	v_fmac_f32_e32 v87, v94, v94
	v_add_f32_e32 v86, v87, v86
	v_add_f32_e32 v96, v103, v86
	v_cvt_pk_bf16_f32 v86, v90, v91
	v_cvt_pk_bf16_f32 v87, v92, v93
	v_cvt_pk_bf16_f32 v88, v88, v89
	v_cvt_pk_bf16_f32 v89, v94, v95
	global_store_dwordx4 v[104:105], v[86:89], off offset:64 sc1
	s_nop 1
	v_mov_b32_e32 v86, v96
	s_nop 1
	v_permlane16_swap_b32_e32 v96, v86
	v_add_f32_e32 v86, v96, v86
	v_mov_b32_e32 v87, v86
	s_nop 1
	v_permlane32_swap_b32_e32 v86, v87
	s_and_saveexec_b64 s[26:27], s[6:7]
	s_cbranch_execz .LBB0_794
	s_add_u32 s28, s57, s24
	s_addc_u32 s29, s58, s25
	v_lshl_add_u64 v[88:89], v[134:135], 2, s[28:29]
	v_add_f32_e32 v86, v86, v87
	global_store_dword v[88:89], v86, off offset:128 sc1
.LBB0_794:
	s_or_b64 exec, exec, s[26:27]
	v_add_f32_e32 v86, v148, v149
	v_fmamk_f32 v86, v86, 0x3a800000, v236
	v_rsq_f32_e32 v86, v86
	v_or_b32_e32 v88, 48, v134
	v_ashrrev_i32_e32 v89, 31, v88
	v_lshlrev_b64 v[88:89], 11, v[88:89]
	v_pk_mul_f32 v[84:85], v[84:85], v[86:87] op_sel_hi:[1,0]
	v_pk_mul_f32 v[82:83], v[82:83], v[86:87] op_sel_hi:[1,0]
	v_pk_mul_f32 v[90:91], v[80:81], v[86:87] op_sel_hi:[1,0]
	v_pk_mul_f32 v[80:81], v[78:79], v[86:87] op_sel_hi:[1,0]
	v_mul_f32_e32 v78, v83, v83
	v_mul_f32_e32 v79, v85, v85
	v_fmac_f32_e32 v78, v82, v82
	v_fmac_f32_e32 v79, v84, v84
	v_add_f32_e32 v78, v78, v79
	v_mul_f32_e32 v79, v81, v81
	v_fmac_f32_e32 v79, v80, v80
	v_add_f32_e32 v78, v79, v78
	v_mul_f32_e32 v79, v91, v91
	v_fmac_f32_e32 v79, v90, v90
	v_lshl_add_u64 v[88:89], s[8:9], 0, v[88:89]
	v_add_f32_e32 v87, v79, v78
	v_lshl_add_u64 v[88:89], v[138:139], 1, v[88:89]
	v_cvt_pk_bf16_f32 v78, v82, v83
	v_cvt_pk_bf16_f32 v79, v84, v85
	v_pk_mul_f32 v[76:77], v[76:77], v[86:87] op_sel_hi:[1,0]
	v_pk_mul_f32 v[74:75], v[74:75], v[86:87] op_sel_hi:[1,0]
	v_cvt_pk_bf16_f32 v80, v80, v81
	v_cvt_pk_bf16_f32 v81, v90, v91
	global_store_dwordx4 v[88:89], v[78:81], off sc1
	s_nop 1
	v_pk_mul_f32 v[78:79], v[72:73], v[86:87] op_sel_hi:[1,0]
	v_pk_mul_f32 v[72:73], v[70:71], v[86:87] op_sel_hi:[1,0]
	v_mul_f32_e32 v70, v75, v75
	v_mul_f32_e32 v71, v77, v77
	v_fmac_f32_e32 v70, v74, v74
	v_fmac_f32_e32 v71, v76, v76
	v_add_f32_e32 v70, v70, v71
	v_mul_f32_e32 v71, v73, v73
	v_fmac_f32_e32 v71, v72, v72
	v_add_f32_e32 v70, v71, v70
	v_mul_f32_e32 v71, v79, v79
	v_fmac_f32_e32 v71, v78, v78
	v_add_f32_e32 v70, v71, v70
	v_add_f32_e32 v80, v87, v70
	v_cvt_pk_bf16_f32 v70, v74, v75
	v_cvt_pk_bf16_f32 v71, v76, v77
	v_cvt_pk_bf16_f32 v72, v72, v73
	v_cvt_pk_bf16_f32 v73, v78, v79
	global_store_dwordx4 v[88:89], v[70:73], off offset:64 sc1
	s_nop 1
	v_mov_b32_e32 v70, v80
	s_nop 1
	v_permlane16_swap_b32_e32 v80, v70
	v_add_f32_e32 v70, v80, v70
	v_mov_b32_e32 v71, v70
	s_nop 1
	v_permlane32_swap_b32_e32 v70, v71
	s_and_saveexec_b64 s[26:27], s[6:7]
	s_cbranch_execz .LBB0_796
	s_add_u32 s28, s57, s24
	s_addc_u32 s29, s58, s25
	v_lshl_add_u64 v[72:73], v[134:135], 2, s[28:29]
	v_add_f32_e32 v70, v70, v71
	global_store_dword v[72:73], v70, off offset:192 sc1
.LBB0_796:
	s_or_b64 exec, exec, s[26:27]
	v_add_f32_e32 v72, v146, v147
	v_fmamk_f32 v72, v72, 0x3a800000, v236
	v_rsq_f32_e32 v72, v72
	v_lshlrev_b64 v[70:71], 11, v[134:135]
	v_lshl_add_u64 v[70:71], s[8:9], 0, v[70:71]
	v_lshl_add_u64 v[70:71], v[138:139], 1, v[70:71]
	v_pk_mul_f32 v[68:69], v[68:69], v[72:73] op_sel_hi:[1,0]
	v_pk_mul_f32 v[66:67], v[66:67], v[72:73] op_sel_hi:[1,0]
	v_pk_mul_f32 v[76:77], v[64:65], v[72:73] op_sel_hi:[1,0]
	v_pk_mul_f32 v[64:65], v[62:63], v[72:73] op_sel_hi:[1,0]
	v_mul_f32_e32 v62, v67, v67
	v_mul_f32_e32 v63, v69, v69
	v_fmac_f32_e32 v62, v66, v66
	v_fmac_f32_e32 v63, v68, v68
	v_add_f32_e32 v62, v62, v63
	v_mul_f32_e32 v63, v65, v65
	v_fmac_f32_e32 v63, v64, v64
	v_add_f32_e32 v62, v63, v62
	v_mul_f32_e32 v63, v77, v77
	v_fmac_f32_e32 v63, v76, v76
	v_add_f32_e32 v73, v63, v62
	v_cvt_pk_bf16_f32 v62, v66, v67
	v_add_co_u32_e32 v66, vcc, s72, v70
	v_cvt_pk_bf16_f32 v63, v68, v69
	v_pk_mul_f32 v[60:61], v[60:61], v[72:73] op_sel_hi:[1,0]
	s_nop 0
	v_addc_co_u32_e32 v67, vcc, 0, v71, vcc
	v_pk_mul_f32 v[58:59], v[58:59], v[72:73] op_sel_hi:[1,0]
	v_cvt_pk_bf16_f32 v64, v64, v65
	v_cvt_pk_bf16_f32 v65, v76, v77
	global_store_dwordx4 v[66:67], v[62:65], off sc1
	s_mov_b64 s[26:27], 0x40000
	v_lshl_add_u64 v[74:75], v[70:71], 0, s[26:27]
	v_pk_mul_f32 v[62:63], v[56:57], v[72:73] op_sel_hi:[1,0]
	v_pk_mul_f32 v[56:57], v[54:55], v[72:73] op_sel_hi:[1,0]
	v_mul_f32_e32 v54, v59, v59
	v_mul_f32_e32 v55, v61, v61
	v_fmac_f32_e32 v54, v58, v58
	v_fmac_f32_e32 v55, v60, v60
	v_add_f32_e32 v54, v54, v55
	v_mul_f32_e32 v55, v57, v57
	v_fmac_f32_e32 v55, v56, v56
	v_add_f32_e32 v54, v55, v54
	v_mul_f32_e32 v55, v63, v63
	v_fmac_f32_e32 v55, v62, v62
	v_add_f32_e32 v54, v55, v54
	v_add_f32_e32 v64, v73, v54
	v_cvt_pk_bf16_f32 v54, v58, v59
	v_cvt_pk_bf16_f32 v55, v60, v61
	v_cvt_pk_bf16_f32 v56, v56, v57
	v_cvt_pk_bf16_f32 v57, v62, v63
	global_store_dwordx4 v[74:75], v[54:57], off offset:64 sc1
	s_nop 1
	v_mov_b32_e32 v54, v64
	s_nop 1
	v_permlane16_swap_b32_e32 v64, v54
	v_add_f32_e32 v54, v64, v54
	v_mov_b32_e32 v55, v54
	s_nop 1
	v_permlane32_swap_b32_e32 v54, v55
	s_and_saveexec_b64 s[26:27], s[6:7]
	s_cbranch_execz .LBB0_798
	s_add_u32 s28, s57, s24
	s_addc_u32 s29, s58, s25
	v_lshl_add_u64 v[56:57], v[134:135], 2, s[28:29]
	v_add_f32_e32 v54, v54, v55
	global_store_dword v[56:57], v54, off offset:512 sc1
.LBB0_798:
	s_or_b64 exec, exec, s[26:27]
	v_add_f32_e32 v54, v144, v145
	v_fmamk_f32 v54, v54, 0x3a800000, v236
	v_rsq_f32_e32 v54, v54
	s_mov_b32 s15, 0x48000
	s_mov_b64 s[26:27], 0x48000
	v_lshl_add_u64 v[56:57], v[136:137], 0, s[26:27]
	v_pk_mul_f32 v[52:53], v[52:53], v[54:55] op_sel_hi:[1,0]
	v_pk_mul_f32 v[50:51], v[50:51], v[54:55] op_sel_hi:[1,0]
	v_pk_mul_f32 v[58:59], v[48:49], v[54:55] op_sel_hi:[1,0]
	v_pk_mul_f32 v[48:49], v[46:47], v[54:55] op_sel_hi:[1,0]
	v_mul_f32_e32 v46, v51, v51
	v_mul_f32_e32 v47, v53, v53
	v_fmac_f32_e32 v46, v50, v50
	v_fmac_f32_e32 v47, v52, v52
	v_add_f32_e32 v46, v46, v47
	v_mul_f32_e32 v47, v49, v49
	v_fmac_f32_e32 v47, v48, v48
	v_add_f32_e32 v46, v47, v46
	v_mul_f32_e32 v47, v59, v59
	v_fmac_f32_e32 v47, v58, v58
	v_add_f32_e32 v55, v47, v46
	v_cvt_pk_bf16_f32 v46, v50, v51
	v_add_co_u32_e32 v50, vcc, s15, v136
	v_cvt_pk_bf16_f32 v47, v52, v53
	v_pk_mul_f32 v[44:45], v[44:45], v[54:55] op_sel_hi:[1,0]
	s_nop 0
	v_addc_co_u32_e32 v51, vcc, 0, v137, vcc
	v_pk_mul_f32 v[42:43], v[42:43], v[54:55] op_sel_hi:[1,0]
	v_cvt_pk_bf16_f32 v48, v48, v49
	v_cvt_pk_bf16_f32 v49, v58, v59
	global_store_dwordx4 v[50:51], v[46:49], off sc1
	s_nop 1
	v_pk_mul_f32 v[46:47], v[40:41], v[54:55] op_sel_hi:[1,0]
	v_pk_mul_f32 v[40:41], v[38:39], v[54:55] op_sel_hi:[1,0]
	v_mul_f32_e32 v38, v43, v43
	v_mul_f32_e32 v39, v45, v45
	v_fmac_f32_e32 v38, v42, v42
	v_fmac_f32_e32 v39, v44, v44
	v_add_f32_e32 v38, v38, v39
	v_mul_f32_e32 v39, v41, v41
	v_fmac_f32_e32 v39, v40, v40
	v_add_f32_e32 v38, v39, v38
	v_mul_f32_e32 v39, v47, v47
	v_fmac_f32_e32 v39, v46, v46
	v_add_f32_e32 v38, v39, v38
	v_add_f32_e32 v48, v55, v38
	v_cvt_pk_bf16_f32 v38, v42, v43
	v_cvt_pk_bf16_f32 v39, v44, v45
	v_cvt_pk_bf16_f32 v40, v40, v41
	v_cvt_pk_bf16_f32 v41, v46, v47
	global_store_dwordx4 v[56:57], v[38:41], off offset:64 sc1
	s_nop 1
	v_mov_b32_e32 v38, v48
	s_nop 1
	v_permlane16_swap_b32_e32 v48, v38
	v_add_f32_e32 v38, v48, v38
	v_mov_b32_e32 v39, v38
	s_nop 1
	v_permlane32_swap_b32_e32 v38, v39
	s_and_saveexec_b64 s[26:27], s[6:7]
	s_cbranch_execz .LBB0_800
	s_add_u32 s28, s57, s24
	s_addc_u32 s29, s58, s25
	v_lshl_add_u64 v[40:41], v[134:135], 2, s[28:29]
	v_add_f32_e32 v38, v38, v39
	global_store_dword v[40:41], v38, off offset:576 sc1
.LBB0_800:
	s_or_b64 exec, exec, s[26:27]
	v_add_f32_e32 v38, v142, v143
	v_fmamk_f32 v38, v38, 0x3a800000, v236
	v_rsq_f32_e32 v38, v38
	s_mov_b32 s15, 0x50000
	s_mov_b64 s[26:27], 0x50000
	v_lshl_add_u64 v[40:41], v[136:137], 0, s[26:27]
	v_pk_mul_f32 v[36:37], v[36:37], v[38:39] op_sel_hi:[1,0]
	v_pk_mul_f32 v[34:35], v[34:35], v[38:39] op_sel_hi:[1,0]
	v_pk_mul_f32 v[42:43], v[32:33], v[38:39] op_sel_hi:[1,0]
	v_pk_mul_f32 v[32:33], v[30:31], v[38:39] op_sel_hi:[1,0]
	v_mul_f32_e32 v30, v35, v35
	v_mul_f32_e32 v31, v37, v37
	v_fmac_f32_e32 v30, v34, v34
	v_fmac_f32_e32 v31, v36, v36
	v_add_f32_e32 v30, v30, v31
	v_mul_f32_e32 v31, v33, v33
	v_fmac_f32_e32 v31, v32, v32
	v_add_f32_e32 v30, v31, v30
	v_mul_f32_e32 v31, v43, v43
	v_fmac_f32_e32 v31, v42, v42
	v_add_f32_e32 v39, v31, v30
	v_cvt_pk_bf16_f32 v30, v34, v35
	v_add_co_u32_e32 v34, vcc, s15, v136
	v_cvt_pk_bf16_f32 v31, v36, v37
	v_pk_mul_f32 v[28:29], v[28:29], v[38:39] op_sel_hi:[1,0]
	s_nop 0
	v_addc_co_u32_e32 v35, vcc, 0, v137, vcc
	v_pk_mul_f32 v[26:27], v[26:27], v[38:39] op_sel_hi:[1,0]
	v_cvt_pk_bf16_f32 v32, v32, v33
	v_cvt_pk_bf16_f32 v33, v42, v43
	global_store_dwordx4 v[34:35], v[30:33], off sc1
	s_nop 1
	v_pk_mul_f32 v[30:31], v[24:25], v[38:39] op_sel_hi:[1,0]
	v_pk_mul_f32 v[24:25], v[22:23], v[38:39] op_sel_hi:[1,0]
	v_mul_f32_e32 v22, v27, v27
	v_mul_f32_e32 v23, v29, v29
	v_fmac_f32_e32 v22, v26, v26
	v_fmac_f32_e32 v23, v28, v28
	v_add_f32_e32 v22, v22, v23
	v_mul_f32_e32 v23, v25, v25
	v_fmac_f32_e32 v23, v24, v24
	v_add_f32_e32 v22, v23, v22
	v_mul_f32_e32 v23, v31, v31
	v_fmac_f32_e32 v23, v30, v30
	v_add_f32_e32 v22, v23, v22
	v_add_f32_e32 v32, v39, v22
	v_cvt_pk_bf16_f32 v22, v26, v27
	v_cvt_pk_bf16_f32 v23, v28, v29
	v_cvt_pk_bf16_f32 v24, v24, v25
	v_cvt_pk_bf16_f32 v25, v30, v31
	global_store_dwordx4 v[40:41], v[22:25], off offset:64 sc1
	s_nop 1
	v_mov_b32_e32 v22, v32
	s_nop 1
	v_permlane16_swap_b32_e32 v32, v22
	v_add_f32_e32 v22, v32, v22
	v_mov_b32_e32 v23, v22
	s_nop 1
	v_permlane32_swap_b32_e32 v22, v23
	s_and_saveexec_b64 s[26:27], s[6:7]
	s_cbranch_execz .LBB0_802
	s_add_u32 s28, s57, s24
	s_addc_u32 s29, s58, s25
	v_lshl_add_u64 v[24:25], v[134:135], 2, s[28:29]
	v_add_f32_e32 v22, v22, v23
	global_store_dword v[24:25], v22, off offset:640 sc1
.LBB0_802:
	s_or_b64 exec, exec, s[26:27]
	v_add_f32_e32 v22, v140, v141
	v_fmamk_f32 v22, v22, 0x3a800000, v236
	v_rsq_f32_e32 v22, v22
	s_mov_b32 s15, 0x58000
	s_mov_b64 s[26:27], 0x58000
	v_lshl_add_u64 v[24:25], v[136:137], 0, s[26:27]
	v_pk_mul_f32 v[20:21], v[20:21], v[22:23] op_sel_hi:[1,0]
	v_pk_mul_f32 v[18:19], v[18:19], v[22:23] op_sel_hi:[1,0]
	v_pk_mul_f32 v[26:27], v[16:17], v[22:23] op_sel_hi:[1,0]
	v_pk_mul_f32 v[16:17], v[14:15], v[22:23] op_sel_hi:[1,0]
	v_mul_f32_e32 v14, v19, v19
	v_mul_f32_e32 v15, v21, v21
	v_fmac_f32_e32 v14, v18, v18
	v_fmac_f32_e32 v15, v20, v20
	v_add_f32_e32 v14, v14, v15
	v_mul_f32_e32 v15, v17, v17
	v_fmac_f32_e32 v15, v16, v16
	v_add_f32_e32 v14, v15, v14
	v_mul_f32_e32 v15, v27, v27
	v_fmac_f32_e32 v15, v26, v26
	v_add_f32_e32 v23, v15, v14
	v_cvt_pk_bf16_f32 v14, v18, v19
	v_add_co_u32_e32 v18, vcc, s15, v136
	v_cvt_pk_bf16_f32 v15, v20, v21
	v_pk_mul_f32 v[12:13], v[12:13], v[22:23] op_sel_hi:[1,0]
	s_nop 0
	v_addc_co_u32_e32 v19, vcc, 0, v137, vcc
	v_pk_mul_f32 v[10:11], v[10:11], v[22:23] op_sel_hi:[1,0]
	v_cvt_pk_bf16_f32 v16, v16, v17
	v_cvt_pk_bf16_f32 v17, v26, v27
	global_store_dwordx4 v[18:19], v[14:17], off sc1
	s_nop 1
	v_pk_mul_f32 v[14:15], v[8:9], v[22:23] op_sel_hi:[1,0]
	v_pk_mul_f32 v[8:9], v[6:7], v[22:23] op_sel_hi:[1,0]
	v_mul_f32_e32 v6, v11, v11
	v_mul_f32_e32 v7, v13, v13
	v_fmac_f32_e32 v6, v10, v10
	v_fmac_f32_e32 v7, v12, v12
	v_add_f32_e32 v6, v6, v7
	v_mul_f32_e32 v7, v9, v9
	v_fmac_f32_e32 v7, v8, v8
	v_add_f32_e32 v6, v7, v6
	v_mul_f32_e32 v7, v15, v15
	v_fmac_f32_e32 v7, v14, v14
	v_add_f32_e32 v6, v7, v6
	v_add_f32_e32 v16, v23, v6
	v_cvt_pk_bf16_f32 v6, v10, v11
	v_cvt_pk_bf16_f32 v7, v12, v13
	v_cvt_pk_bf16_f32 v8, v8, v9
	v_cvt_pk_bf16_f32 v9, v14, v15
	global_store_dwordx4 v[24:25], v[6:9], off offset:64 sc1
	s_nop 1
	v_mov_b32_e32 v6, v16
	s_nop 1
	v_permlane16_swap_b32_e32 v16, v6
	v_add_f32_e32 v6, v16, v6
	v_mov_b32_e32 v7, v6
	s_nop 1
	v_permlane32_swap_b32_e32 v6, v7
	s_and_saveexec_b64 s[26:27], s[6:7]
	s_cbranch_execz .LBB0_804
	s_add_u32 s24, s57, s24
	s_addc_u32 s25, s58, s25
	v_lshl_add_u64 v[8:9], v[134:135], 2, s[24:25]
	v_add_f32_e32 v6, v6, v7
	global_store_dword v[8:9], v6, off offset:704 sc1

.LBB0_1035:
	s_lshl_b32 s8, s79, 2
	s_or_b32 s8, s8, s66
	s_ashr_i32 s9, s8, 31
	v_cndmask_b32_e64 v138, 0, 1, s[22:23]
	s_lshl_b64 s[40:41], s[8:9], 14
	v_cmp_ne_u32_e64 s[8:9], 1, v138
	s_andn2_b64 vcc, exec, s[22:23]
	s_cbranch_vccnz .LBB0_1039
	v_mov_b32_e32 v138, v232
	s_nop 1
	v_permlane16_swap_b32_e32 v232, v138
	v_add_f32_e32 v138, v232, v138
	v_mov_b32_e32 v139, v138
	s_nop 1
	v_permlane32_swap_b32_e32 v138, v139
	s_and_saveexec_b64 s[42:43], s[4:5]
	s_cbranch_execz .LBB0_1038
	s_add_u32 s44, s72, s40
	s_addc_u32 s45, s73, s41
	v_lshl_add_u64 v[140:141], v[198:199], 2, s[44:45]
	v_add_f32_e32 v138, v138, v139
	global_store_dword v[140:141], v138, off sc1

.LBB0_1048:
	v_mov_b32_e32 v110, v142
	s_nop 1
	v_permlane16_swap_b32_e32 v142, v110
	v_add_f32_e32 v110, v142, v110
	v_mov_b32_e32 v111, v110
	s_nop 1
	v_permlane32_swap_b32_e32 v110, v111
	s_and_saveexec_b64 s[42:43], s[4:5]
	s_cbranch_execz .LBB0_1050
	s_add_u32 s44, s72, s40
	s_addc_u32 s45, s73, s41
	v_lshl_add_u64 v[112:113], v[198:199], 2, s[44:45]
	v_add_f32_e32 v110, v110, v111
	global_store_dword v[112:113], v110, off offset:64 sc1

.LBB0_1060:
	v_mov_b32_e32 v86, v118
	s_nop 1
	v_permlane16_swap_b32_e32 v118, v86
	v_add_f32_e32 v86, v118, v86
	v_mov_b32_e32 v87, v86
	s_nop 1
	v_permlane32_swap_b32_e32 v86, v87
	s_and_saveexec_b64 s[42:43], s[4:5]
	s_cbranch_execz .LBB0_1062
	s_add_u32 s44, s72, s40
	s_addc_u32 s45, s73, s41
	v_lshl_add_u64 v[88:89], v[198:199], 2, s[44:45]
	v_add_f32_e32 v86, v86, v87
	global_store_dword v[88:89], v86, off offset:128 sc1

.LBB0_1072:
	v_mov_b32_e32 v70, v94
	s_nop 1
	v_permlane16_swap_b32_e32 v94, v70
	v_add_f32_e32 v70, v94, v70
	v_mov_b32_e32 v71, v70
	s_nop 1
	v_permlane32_swap_b32_e32 v70, v71
	s_and_saveexec_b64 s[42:43], s[4:5]
	s_cbranch_execz .LBB0_1074
	s_add_u32 s44, s72, s40
	s_addc_u32 s45, s73, s41
	v_lshl_add_u64 v[72:73], v[198:199], 2, s[44:45]
	v_add_f32_e32 v70, v70, v71
	global_store_dword v[72:73], v70, off offset:192 sc1

.LBB0_1084:
	v_mov_b32_e32 v54, v74
	s_nop 1
	v_permlane16_swap_b32_e32 v74, v54
	v_add_f32_e32 v54, v74, v54
	v_mov_b32_e32 v55, v54
	s_nop 1
	v_permlane32_swap_b32_e32 v54, v55
	s_and_saveexec_b64 s[42:43], s[4:5]
	s_cbranch_execz .LBB0_1086
	s_add_u32 s44, s72, s40
	s_addc_u32 s45, s73, s41
	v_lshl_add_u64 v[56:57], v[198:199], 2, s[44:45]
	v_add_f32_e32 v54, v54, v55
	global_store_dword v[56:57], v54, off offset:512 sc1

.LBB0_1096:
	v_mov_b32_e32 v38, v58
	s_nop 1
	v_permlane16_swap_b32_e32 v58, v38
	v_add_f32_e32 v38, v58, v38
	v_mov_b32_e32 v39, v38
	s_nop 1
	v_permlane32_swap_b32_e32 v38, v39
	s_and_saveexec_b64 s[42:43], s[4:5]
	s_cbranch_execz .LBB0_1098
	s_add_u32 s44, s72, s40
	s_addc_u32 s45, s73, s41
	v_lshl_add_u64 v[40:41], v[198:199], 2, s[44:45]
	v_add_f32_e32 v38, v38, v39
	global_store_dword v[40:41], v38, off offset:576 sc1

.LBB0_1108:
	v_mov_b32_e32 v22, v42
	s_nop 1
	v_permlane16_swap_b32_e32 v42, v22
	v_add_f32_e32 v22, v42, v22
	v_mov_b32_e32 v23, v22
	s_nop 1
	v_permlane32_swap_b32_e32 v22, v23
	s_and_saveexec_b64 s[42:43], s[4:5]
	s_cbranch_execz .LBB0_1110
	s_add_u32 s44, s72, s40
	s_addc_u32 s45, s73, s41
	v_lshl_add_u64 v[24:25], v[198:199], 2, s[44:45]
	v_add_f32_e32 v22, v22, v23
	global_store_dword v[24:25], v22, off offset:640 sc1

.LBB0_1124:
	v_mov_b32_e32 v6, v24
	s_nop 1
	v_permlane16_swap_b32_e32 v24, v6
	v_add_f32_e32 v6, v24, v6
	v_mov_b32_e32 v7, v6
	s_nop 1
	v_permlane32_swap_b32_e32 v6, v7
	s_and_saveexec_b64 s[6:7], s[4:5]
	s_cbranch_execz .LBB0_1126
	s_add_u32 s8, s72, s40
	s_addc_u32 s9, s73, s41
	v_lshl_add_u64 v[8:9], v[198:199], 2, s[8:9]
	v_add_f32_e32 v6, v6, v7
	global_store_dword v[8:9], v6, off offset:704 sc1

.LBB0_1149:
	s_mov_b64 s[4:5], exec
	s_waitcnt lgkmcnt(0)
	s_waitcnt vmcnt(0)
	v_mbcnt_lo_u32_b32 v3, s4, 0
	v_mbcnt_hi_u32_b32 v3, s5, v3
	v_cmp_eq_u32_e32 vcc, 0, v3
	s_and_saveexec_b64 s[6:7], vcc
	s_cbranch_execz .LBB0_1151
	s_bcnt1_i32_b64 s4, s[4:5]
	v_mov_b32_e32 v5, s4
	v_readlane_b32 s4, v253, 9
	v_readlane_b32 s5, v253, 10
	s_nop 4
	global_atomic_add v5, v4, v5, s[4:5] sc0
